# grid barrier sites 1-16: one arrival counter per site, leaders add after L2 write-back, every workgroup spins for count == populated XCDs
# speedup vs baseline: 1.0071x; 1.0036x over previous
.LBB0_211:
	s_or_b64 exec, exec, s[8:9]
	v_cvt_f32_u32_e32 v4, v2
	s_waitcnt vmcnt(0)
	v_readfirstlane_b32 s6, v3
	v_sub_u32_e32 v3, 0, v2
	v_rcp_iflag_f32_e32 v4, v4
	v_add_u32_e32 v5, s6, v1
	v_mul_f32_e32 v4, 0x4f7ffffe, v4
	v_cvt_u32_f32_e32 v4, v4
	v_mul_lo_u32 v1, v3, v4
	v_mul_hi_u32 v1, v4, v1
	v_add_u32_e32 v1, v4, v1
	v_mul_hi_u32 v1, v5, v1
	v_mul_lo_u32 v3, v1, v2
	v_sub_u32_e32 v3, v5, v3
	v_add_u32_e32 v4, 1, v1
	v_cmp_ge_u32_e32 vcc, v3, v2
	s_nop 1
	v_cndmask_b32_e32 v1, v1, v4, vcc
	v_sub_u32_e32 v4, v3, v2
	v_cndmask_b32_e32 v3, v3, v4, vcc
	v_add_u32_e32 v4, 1, v1
	v_cmp_ge_u32_e32 vcc, v3, v2
	v_add_u32_e32 v3, 1, v5
	s_nop 0
	v_cndmask_b32_e32 v1, v1, v4, vcc
	v_mul_lo_u32 v4, v2, v1
	v_add_u32_e32 v2, v4, v2
	v_cmp_ne_u32_e32 vcc, v3, v2
	s_and_saveexec_b64 s[6:7], vcc
	s_xor_b64 s[6:7], exec, s[6:7]
	s_cbranch_execz .LBB0_225
	s_waitcnt lgkmcnt(0)
	buffer_inv sc1
	v_mov_b32_e32 v1, v0
	v_mov_b32_e32 v0, 0
	s_add_u32 s12, s86, 0xe7b1010
	s_addc_u32 s13, s87, 0
	global_load_dword v0, v0, s[12:13] sc1
	s_waitcnt vmcnt(0)
	v_cmp_ne_u32_e32 vcc, v0, v1
	s_and_saveexec_b64 s[8:9], vcc
	s_cbranch_execz .LBB0_224
	s_add_u32 s10, s86, 0xe7b1200
	s_addc_u32 s11, s87, 0
	s_mov_b32 s26, 1
	s_mov_b64 s[14:15], 0
	v_mov_b32_e32 v0, 0
	s_branch .LBB0_215

.LBB0_219:
	global_load_dword v2, v0, s[12:13] sc1
	s_add_i32 s26, s26, 1
	s_mov_b64 s[20:21], -1
	s_waitcnt vmcnt(0)
	v_cmp_eq_u32_e32 vcc, v2, v1
	s_orn2_b64 s[18:19], vcc, exec
	s_branch .LBB0_214

.LBB0_225:
	s_andn2_saveexec_b64 s[6:7], s[6:7]
	s_cbranch_execz .LBB0_245
	s_mov_b64 s[6:7], exec
	buffer_wbl2 sc1
	buffer_inv sc1
	s_waitcnt lgkmcnt(0)
	s_waitcnt vmcnt(0)
	v_readfirstlane_b32 s99, v0
	s_add_u32 s100, s86, 0xe7b1010
	s_addc_u32 s101, s87, 0
	v_mov_b32_e32 v0, 0
	v_mov_b32_e32 v2, 1
	global_atomic_add v0, v2, s[100:101]
	s_mov_b32 s98, 0
.Lxb_spin_1:
	s_sleep 1
	global_load_dword v1, v0, s[100:101] sc1
	s_add_i32 s98, s98, 1
	s_waitcnt vmcnt(0)
	v_cmp_eq_u32_e32 vcc, s99, v1
	s_cbranch_vccnz .Lxb_done_1
	s_cmp_lt_u32 s98, 0x8000
	s_cbranch_scc1 .Lxb_spin_1
.Lxb_done_1:
	s_waitcnt vmcnt(0)
.LBB0_245:
	s_or_b64 exec, exec, s[0:1]
	v_bfe_u32 v196, v128, 3, 3
	s_waitcnt lgkmcnt(0)
	v_bfe_u32 v0, v128, 4, 2
	v_bfe_u32 v191, v128, 1, 3
	s_cmpk_gt_i32 s2, 0x1af
	v_bfe_u32 v193, v128, 3, 5
	v_lshrrev_b32_e32 v190, 3, v128
	v_and_b32_e32 v189, 15, v128
	v_bitop3_b32 v192, v0, v191, 4 bitop3:0x36
	v_lshlrev_b32_e32 v133, 11, v196
	s_barrier
	s_cbranch_scc1 .LBB0_295
	v_and_b32_e32 v0, 0x78, v190
	v_add_u32_e32 v1, 64, v0
	v_or_b32_e32 v2, v1, v196
	v_or_b32_e32 v3, 0x80, v190
	v_add_u32_e32 v0, 0xc0, v0
	v_lshrrev_b32_e32 v7, 1, v2
	v_or_b32_e32 v4, v0, v196
	v_xor_b32_e32 v8, v7, v128
	v_lshrrev_b32_e32 v9, 1, v3
	v_lshlrev_b32_e32 v15, 2, v1
	v_lshlrev_b32_e32 v8, 4, v8
	v_xor_b32_e32 v10, v9, v128
	v_lshrrev_b32_e32 v11, 1, v4
	v_lshrrev_b32_e32 v13, 1, v128
	v_and_b32_e32 v15, 0x80, v15
	v_and_b32_e32 v7, 0x60, v7
	v_bitop3_b32 v1, v1, 31, v196 bitop3:0xc8
	v_lshlrev_b32_e32 v0, 2, v0
	v_and_b32_e32 v8, 0x70, v8
	v_lshlrev_b32_e32 v10, 4, v10
	v_xor_b32_e32 v12, v11, v128
	v_and_b32_e32 v13, 0x80, v13
	v_or3_b32 v1, v15, v7, v1
	v_and_b32_e32 v7, 0x60, v9
	v_and_b32_e32 v0, 0x80, v0
	v_and_b32_e32 v9, 0xe0, v11
	v_xor_b32_e32 v6, v188, v128
	v_and_b32_e32 v10, 0x70, v10
	v_lshlrev_b32_e32 v12, 4, v12
	v_or3_b32 v7, v13, v7, v193
	v_add_u32_e32 v9, v9, v0
	v_lshl_or_b32 v2, v2, 11, v8
	v_lshl_or_b32 v1, v1, 11, v8
	v_lshlrev_b32_e32 v6, 4, v6
	v_and_b32_e32 v12, 0x70, v12
	v_and_b32_e32 v14, 32, v188
	v_and_or_b32 v9, v4, 31, v9
	v_add_u32_e32 v138, 0xc3b1000, v2
	v_lshl_or_b32 v2, v3, 11, v10
	v_add_u32_e32 v146, 0x1971000, v1
	v_lshl_or_b32 v1, v7, 11, v10
	s_add_u32 s6, s86, 0x196c000
	v_and_b32_e32 v6, 0x70, v6
	v_or3_b32 v14, v14, v13, v193
	v_add_u32_e32 v140, 0xc3b1000, v2
	v_lshl_or_b32 v2, v4, 11, v12
	v_add_u32_e32 v148, 0x1971000, v1
	v_lshl_or_b32 v1, v9, 11, v12
	s_addc_u32 s7, s87, 0
	v_add_u32_e32 v142, 0xc3b1000, v2
	v_lshl_or_b32 v2, v14, 11, v6
	v_add_u32_e32 v150, 0x1971000, v1
	v_lshl_or_b32 v1, v130, 14, v133
	v_add_u32_e32 v144, 0x1971000, v2
	s_add_u32 s8, s86, 0x69b1000
	v_or_b32_e32 v2, v1, v8
	v_or_b32_e32 v1, v1, v12
	v_lshlrev_b32_e32 v5, 11, v190
	s_addc_u32 s9, s87, 0
	v_add_u32_e32 v156, 0xc411000, v1
	v_mov_b32_e32 v1, 0x78
	s_add_u32 s10, s86, 0x3831000
	v_add_u32_e32 v152, 0xc3d1000, v2
	v_or_b32_e32 v2, v5, v10
	v_bitop3_b32 v1, v190, 7, v1 bitop3:0xe0
	s_addc_u32 s11, s87, 0
	v_add_u32_e32 v154, 0xc3f1000, v2
	v_add_u32_e32 v2, 64, v1
	v_add_u32_e32 v1, 0xc0, v1
	s_add_u32 s12, s86, 0x4a31000
	v_lshlrev_b16_e32 v3, 3, v130
	v_lshrrev_b32_e32 v1, 1, v1
	s_addc_u32 s13, s87, 0
	v_lshrrev_b32_e32 v2, 1, v2
	v_bitop3_b16 v3, v3, v190, 7 bitop3:0xf8
	v_and_b32_e32 v1, 0xe0, v1
	s_add_u32 s14, s86, 0x80
	v_and_b32_e32 v2, 0x60, v2
	v_and_b32_e32 v3, 31, v3
	v_add_u32_e32 v0, v0, v1
	v_bitop3_b32 v11, v188, v191, 3 bitop3:0x6c
	s_addc_u32 s15, s87, 0
	v_or3_b32 v2, v15, v2, v3
	v_or_b32_e32 v0, v0, v3
	v_lshlrev_b32_e32 v129, 4, v11
	v_or_b32_e32 v11, v5, v6
	v_lshl_or_b32 v2, v2, 11, v8
	v_lshl_or_b32 v0, v0, 11, v12
	s_add_u32 s18, s86, 0x4eb1010
	v_lshlrev_b32_e32 v135, 4, v192
	v_add_u32_e32 v134, 0xc3b1000, v11
	v_mov_b32_e32 v137, 0
	v_add_u32_e32 v158, 0x1971000, v2
	v_add_u32_e32 v160, 0x1971000, v0
	s_addc_u32 s19, s87, 0
	v_mov_b32_e32 v139, 0x8000
	s_mov_b32 s91, 0
	s_mov_b32 s20, 0x60b0000
	s_mov_b32 s21, 0x60b2000
	s_movk_i32 s24, 0x300
	s_mov_b32 s25, 0x5330000
	s_mov_b32 s26, 0x5333000
	s_movk_i32 s27, 0x900
	v_mov_b32_e32 v141, 0x358637bd
	s_mov_b32 s28, 0x800000
	s_mov_b64 s[92:93], 0x1000
	s_movk_i32 s29, 0x1000
	v_mov_b32_e32 v143, 4
	v_mov_b32_e32 v145, 0x80
	v_mov_b32_e32 v147, 0x780
	v_mov_b32_e32 v149, 0x100
	v_mov_b32_e32 v151, 0x3e38aa3b
	s_mov_b32 s30, s2
	s_branch .LBB0_248

.LBB0_414:
	s_or_b64 exec, exec, s[8:9]
	v_cvt_f32_u32_e32 v4, v2
	s_waitcnt vmcnt(0)
	v_readfirstlane_b32 s6, v3
	v_sub_u32_e32 v3, 0, v2
	v_rcp_iflag_f32_e32 v4, v4
	v_add_u32_e32 v5, s6, v1
	v_mul_f32_e32 v4, 0x4f7ffffe, v4
	v_cvt_u32_f32_e32 v4, v4
	v_mul_lo_u32 v1, v3, v4
	v_mul_hi_u32 v1, v4, v1
	v_add_u32_e32 v1, v4, v1
	v_mul_hi_u32 v1, v5, v1
	v_mul_lo_u32 v3, v1, v2
	v_sub_u32_e32 v3, v5, v3
	v_add_u32_e32 v4, 1, v1
	v_cmp_ge_u32_e32 vcc, v3, v2
	s_nop 1
	v_cndmask_b32_e32 v1, v1, v4, vcc
	v_sub_u32_e32 v4, v3, v2
	v_cndmask_b32_e32 v3, v3, v4, vcc
	v_add_u32_e32 v4, 1, v1
	v_cmp_ge_u32_e32 vcc, v3, v2
	v_add_u32_e32 v3, 1, v5
	s_nop 0
	v_cndmask_b32_e32 v1, v1, v4, vcc
	v_mul_lo_u32 v4, v2, v1
	v_add_u32_e32 v2, v4, v2
	v_cmp_ne_u32_e32 vcc, v3, v2
	s_and_saveexec_b64 s[6:7], vcc
	s_xor_b64 s[6:7], exec, s[6:7]
	s_cbranch_execz .LBB0_428
	s_waitcnt lgkmcnt(0)
	buffer_inv sc1
	v_mov_b32_e32 v1, v0
	v_mov_b32_e32 v0, 0
	s_add_u32 s12, s86, 0xe7b1020
	s_addc_u32 s13, s87, 0
	global_load_dword v0, v0, s[12:13] sc1
	s_waitcnt vmcnt(0)
	v_cmp_ne_u32_e32 vcc, v0, v1
	s_and_saveexec_b64 s[8:9], vcc
	s_cbranch_execz .LBB0_427
	s_add_u32 s10, s86, 0xe7b1200
	s_addc_u32 s11, s87, 0
	s_mov_b32 s26, 1
	s_mov_b64 s[14:15], 0
	v_mov_b32_e32 v0, 0
	s_branch .LBB0_418

.LBB0_428:
	s_andn2_saveexec_b64 s[6:7], s[6:7]
	s_cbranch_execz .LBB0_448
	s_mov_b64 s[6:7], exec
	buffer_wbl2 sc1
	buffer_inv sc1
	s_waitcnt lgkmcnt(0)
	s_waitcnt vmcnt(0)
	v_readfirstlane_b32 s99, v0
	s_add_u32 s100, s86, 0xe7b1020
	s_addc_u32 s101, s87, 0
	v_mov_b32_e32 v0, 0
	v_mov_b32_e32 v2, 1
	global_atomic_add v0, v2, s[100:101]
	s_mov_b32 s98, 0

.Lxb_done_2:
	s_waitcnt vmcnt(0)
.LBB0_448:
	s_or_b64 exec, exec, s[0:1]
	s_lshl_b32 s33, s2, 1
	s_cmpk_lt_i32 s33, 0x900
	s_cselect_b64 s[12:13], -1, 0
	s_cmpk_gt_i32 s33, 0x8ff
	s_movk_i32 s16, 0x900
	s_waitcnt lgkmcnt(0)
	s_barrier
	s_cbranch_scc1 .LBB0_484
	v_and_b32_e32 v5, 7, v128
	v_mul_u32_u24_e32 v6, 0x90, v193
	v_lshlrev_b32_e32 v2, 4, v5
	v_add3_u32 v123, v194, v6, v2
	v_lshrrev_b32_e32 v6, 1, v128
	v_bfe_u32 v1, v128, 5, 1
	v_and_b32_e32 v6, 64, v6
	v_and_b32_e32 v3, 31, v128
	v_and_b32_e32 v4, 64, v128
	v_lshlrev_b32_e32 v129, 3, v1
	v_lshl_or_b32 v1, v1, 2, v6
	s_movk_i32 s0, 0x210
	v_or_b32_e32 v7, v6, v3
	v_mad_u32_u24 v1, v1, s0, v194
	v_lshlrev_b32_e32 v4, 2, v4
	v_lshlrev_b32_e32 v3, 2, v3
	v_add3_u32 v166, v1, v4, v3
	v_add_u32_e32 v1, 0x10800, v194
	v_bfe_u32 v168, v128, 1, 7
	v_and_b32_e32 v3, 1, v128
	v_mov_b32_e32 v97, 0
	v_lshl_add_u32 v167, v193, 2, v1
	v_lshl_add_u32 v169, v168, 2, v1
	v_cmp_eq_u32_e64 s[6:7], 1, v3
	v_mul_u32_u24_e32 v1, 48, v3
	v_lshlrev_b32_e32 v3, 4, v128
	v_lshlrev_b32_e32 v96, 9, v193
	v_and_b32_e32 v8, 0x5f, v128
	v_and_b32_e32 v4, 0x7e0, v3
	v_mov_b32_e32 v3, v97
	s_add_u32 s14, s86, 0x196e000
	v_mul_u32_u24_e32 v165, 0x90, v8
	v_mad_u32_u24 v170, v168, s0, v194
	v_lshl_add_u64 v[100:101], s[86:87], 0, v[2:3]
	s_mov_b64 s[0:1], 0x60b1000
	v_lshl_add_u64 v[8:9], s[86:87], 0, v[96:97]
	s_addc_u32 s15, s87, 0
	v_lshlrev_b32_e32 v0, 3, v5
	v_cmp_eq_u32_e64 s[4:5], 0, v5
	v_mov_b32_e32 v5, v97
	v_lshl_add_u64 v[102:103], v[100:101], 0, s[0:1]
	v_lshl_add_u64 v[8:9], v[8:9], 0, v[2:3]
	s_mov_b64 s[0:1], 0x1d31000
	v_lshl_add_u64 v[98:99], s[14:15], 0, v[4:5]
	v_mul_u32_u24_e32 v4, 0x300, v193
	v_lshl_add_u64 v[104:105], v[8:9], 0, s[0:1]
	v_lshlrev_b32_e32 v8, 1, v1
	v_mov_b32_e32 v9, v97
	v_lshl_add_u64 v[8:9], s[86:87], 0, v[8:9]
	s_mov_b64 s[0:1], 0x86f1000
	v_lshl_add_u64 v[10:11], s[86:87], 0, v[4:5]
	v_lshl_add_u64 v[108:109], v[8:9], 0, s[0:1]
	v_lshl_add_u64 v[10:11], v[10:11], 0, v[2:3]
	s_mov_b64 s[0:1], 0x1c71000
	v_lshlrev_b32_e32 v6, 2, v1
	v_lshl_add_u64 v[110:111], v[10:11], 0, s[0:1]
	s_mov_b64 s[0:1], 0x6bf1000
	v_bfe_u32 v1, v128, 6, 2
	v_readlane_b32 s36, v252, 16
	v_lshl_add_u64 v[114:115], v[8:9], 0, s[0:1]
	v_mul_u32_u24_e32 v3, 0x4200, v1
	v_lshlrev_b32_e32 v5, 2, v131
	s_movk_i32 s0, 0x100
	v_mul_u32_u24_e32 v164, 0x90, v7
	s_add_u32 s18, s86, 0x69b1000
	v_mov_b32_e32 v7, v97
	v_readlane_b32 s38, v252, 18
	v_readlane_b32 s39, v252, 19
	v_readlane_b32 s40, v252, 20
	v_readlane_b32 s41, v252, 21
	v_or_b32_e32 v96, v96, v2
	v_or3_b32 v212, v3, v5, s0
	v_mul_u32_u24_e32 v3, 0x1200, v131
	v_add_u32_e32 v211, v170, v6
	s_addc_u32 s19, s87, 0
	v_lshl_add_u64 v[106:107], s[40:41], 0, v[6:7]
	v_lshl_add_u64 v[112:113], s[38:39], 0, v[6:7]
	v_lshl_add_u64 v[116:117], s[86:87], 0, v[96:97]
	v_mul_hi_u32_u24_e32 v7, 0x1200, v131
	v_lshl_or_b32 v6, v1, 6, v3
	v_or_b32_e32 v96, v2, v4
	s_add_u32 s72, s86, 0x5331000
	v_lshl_add_u64 v[6:7], s[86:87], 0, v[6:7]
	s_mov_b64 s[0:1], 0xa1f1008
	v_lshl_add_u64 v[120:121], s[86:87], 0, v[96:97]
	v_lshlrev_b32_e32 v96, 1, v0
	v_mbcnt_lo_u32_b32 v0, -1, 0
	s_movk_i32 s17, 0xc0
	v_add_u32_e32 v171, 0xc0, v170
	v_add_u32_e32 v172, 0xc4, v170
	v_add_u32_e32 v173, 0xc8, v170
	v_add_u32_e32 v174, 0xcc, v170
	v_add_u32_e32 v175, 0xd0, v170
	v_add_u32_e32 v176, 0xd4, v170
	v_add_u32_e32 v177, 0xd8, v170
	v_add_u32_e32 v178, 0xdc, v170
	v_add_u32_e32 v179, 0xe0, v170
	v_add_u32_e32 v180, 0xe4, v170
	v_add_u32_e32 v181, 0xe8, v170
	v_add_u32_e32 v182, 0xec, v170
	v_add_u32_e32 v183, 0xf0, v170
	v_add_u32_e32 v184, 0xf4, v170
	v_add_u32_e32 v185, 0xf8, v170
	v_add_u32_e32 v186, 0xfc, v170
	v_add_u32_e32 v187, 4, v170
	v_add_u32_e32 v197, 8, v170
	v_add_u32_e32 v198, 12, v170
	v_add_u32_e32 v199, 16, v170
	v_add_u32_e32 v200, 20, v170
	v_add_u32_e32 v201, 24, v170
	v_add_u32_e32 v202, 28, v170
	v_add_u32_e32 v203, 32, v170
	v_add_u32_e32 v204, 36, v170
	v_add_u32_e32 v205, 40, v170
	v_add_u32_e32 v206, 44, v170
	v_add_u32_e32 v207, 48, v170
	v_add_u32_e32 v208, 52, v170
	v_add_u32_e32 v209, 56, v170
	v_add_u32_e32 v210, 60, v170
	s_addc_u32 s73, s87, 0
	s_lshl_b32 s20, s22, 1
	v_lshlrev_b32_e32 v213, 7, v1
	v_lshl_add_u64 v[118:119], v[6:7], 0, s[0:1]
	v_mov_b32_e32 v214, 0x80
	v_mov_b32_e32 v215, 0x780
	v_mov_b32_e32 v216, 0x100
	s_mov_b32 s21, 0xc000
	v_mov_b32_e32 v217, 0x358637bd
	s_mov_b32 s70, 0x3b800000
	s_mov_b32 s24, 0x800000
	s_mov_b32 s25, 0x18000
	s_mov_b32 s26, 0x12000
	v_mbcnt_hi_u32_b32 v218, -1, v0
	s_mov_b32 s27, s33
	v_readlane_b32 s37, v252, 17
	v_readlane_b32 s42, v252, 22
	v_readlane_b32 s43, v252, 23
	v_readlane_b32 s44, v252, 24
	v_readlane_b32 s45, v252, 25
	v_readlane_b32 s46, v252, 26
	v_readlane_b32 s47, v252, 27
	v_readlane_b32 s48, v252, 28
	v_readlane_b32 s49, v252, 29
	v_readlane_b32 s50, v252, 30
	v_readlane_b32 s51, v252, 31
	s_branch .LBB0_452

.LBB0_502:
	s_or_b64 exec, exec, s[8:9]
	v_cvt_f32_u32_e32 v4, v2
	s_waitcnt vmcnt(0)
	v_readfirstlane_b32 s6, v3
	v_sub_u32_e32 v3, 0, v2
	v_rcp_iflag_f32_e32 v4, v4
	v_add_u32_e32 v5, s6, v1
	v_mul_f32_e32 v4, 0x4f7ffffe, v4
	v_cvt_u32_f32_e32 v4, v4
	v_mul_lo_u32 v1, v3, v4
	v_mul_hi_u32 v1, v4, v1
	v_add_u32_e32 v1, v4, v1
	v_mul_hi_u32 v1, v5, v1
	v_mul_lo_u32 v3, v1, v2
	v_sub_u32_e32 v3, v5, v3
	v_add_u32_e32 v4, 1, v1
	v_cmp_ge_u32_e32 vcc, v3, v2
	s_nop 1
	v_cndmask_b32_e32 v1, v1, v4, vcc
	v_sub_u32_e32 v4, v3, v2
	v_cndmask_b32_e32 v3, v3, v4, vcc
	v_add_u32_e32 v4, 1, v1
	v_cmp_ge_u32_e32 vcc, v3, v2
	v_add_u32_e32 v3, 1, v5
	s_nop 0
	v_cndmask_b32_e32 v1, v1, v4, vcc
	v_mul_lo_u32 v4, v2, v1
	v_add_u32_e32 v2, v4, v2
	v_cmp_ne_u32_e32 vcc, v3, v2
	s_and_saveexec_b64 s[6:7], vcc
	s_xor_b64 s[6:7], exec, s[6:7]
	s_cbranch_execz .LBB0_516
	s_waitcnt lgkmcnt(0)
	buffer_inv sc1
	v_mov_b32_e32 v1, v0
	v_mov_b32_e32 v0, 0
	s_add_u32 s14, s86, 0xe7b1030
	s_addc_u32 s15, s87, 0
	global_load_dword v0, v0, s[14:15] sc1
	s_waitcnt vmcnt(0)
	v_cmp_ne_u32_e32 vcc, v0, v1
	s_and_saveexec_b64 s[8:9], vcc
	s_cbranch_execz .LBB0_515
	s_add_u32 s10, s86, 0xe7b1200
	s_addc_u32 s11, s87, 0
	s_mov_b32 s28, 1
	s_mov_b64 s[16:17], 0
	v_mov_b32_e32 v0, 0
	s_branch .LBB0_506

.LBB0_510:
	global_load_dword v2, v0, s[14:15] sc1
	s_add_i32 s28, s28, 1
	s_mov_b64 s[24:25], -1
	s_waitcnt vmcnt(0)
	v_cmp_eq_u32_e32 vcc, v2, v1
	s_orn2_b64 s[20:21], vcc, exec
	s_branch .LBB0_505

.LBB0_516:
	s_andn2_saveexec_b64 s[6:7], s[6:7]
	s_cbranch_execz .LBB0_536
	s_mov_b64 s[6:7], exec
	buffer_wbl2 sc1
	buffer_inv sc1
	s_waitcnt lgkmcnt(0)
	s_waitcnt vmcnt(0)
	v_readfirstlane_b32 s99, v0
	s_add_u32 s100, s86, 0xe7b1030
	s_addc_u32 s101, s87, 0
	v_mov_b32_e32 v0, 0
	v_mov_b32_e32 v2, 1
	global_atomic_add v0, v2, s[100:101]
	s_mov_b32 s98, 0

.Lxb_done_3:
	s_waitcnt vmcnt(0)
.LBB0_536:
	s_or_b64 exec, exec, s[0:1]
	s_andn2_b64 vcc, exec, s[12:13]
	s_waitcnt lgkmcnt(0)
	s_barrier
	s_cbranch_vccnz .LBB0_587
	v_bfe_u32 v3, v128, 6, 2
	v_lshlrev_b32_e32 v4, 3, v128
	v_mul_u32_u24_e32 v0, 0x5000, v195
	v_lshlrev_b32_e32 v9, 5, v3
	v_and_b32_e32 v4, 56, v4
	v_mul_u32_u24_e32 v3, 0x1200, v3
	s_mov_b32 s1, 0x10000
	v_and_b32_e32 v7, 31, v128
	v_lshlrev_b32_e32 v8, 1, v4
	s_movk_i32 s0, 0x90
	v_add3_u32 v0, v0, v3, s1
	v_mad_u32_u24 v143, v7, s0, v0
	v_or_b32_e32 v145, v0, v8
	v_or_b32_e32 v0, v9, v196
	v_or_b32_e32 v10, v9, v7
	v_lshlrev_b32_e32 v138, 10, v0
	v_mul_u32_u24_e32 v0, 0x1556, v128
	v_mov_b32_e32 v9, 12
	v_lshlrev_b32_e32 v2, 9, v10
	v_mul_u32_u24_e32 v12, 0x48, v190
	v_mul_u32_u24_e32 v3, 0x300, v10
	v_mul_lo_u16_sdwa v10, v0, v9 dst_sel:DWORD dst_unused:UNUSED_PAD src0_sel:WORD_1 src1_sel:DWORD
	v_lshl_add_u32 v139, v12, 1, v8
	v_sub_u16_e32 v12, v128, v10
	v_add_u16_e32 v10, 0x200, v128
	v_mul_u32_u24_e32 v13, 0x1556, v10
	s_movk_i32 s0, 0x300
	v_mul_lo_u16_sdwa v9, v13, v9 dst_sel:DWORD dst_unused:UNUSED_PAD src0_sel:WORD_1 src1_sel:DWORD
	v_lshlrev_b32_e32 v1, 7, v195
	v_sub_u16_e32 v9, v10, v9
	v_mul_u32_u24_sdwa v10, v0, s0 dst_sel:DWORD dst_unused:UNUSED_PAD src0_sel:WORD_1 src1_sel:DWORD
	v_lshlrev_b16_e32 v146, 3, v12
	v_mul_u32_u24_sdwa v148, v13, s0 dst_sel:DWORD dst_unused:UNUSED_PAD src0_sel:WORD_1 src1_sel:DWORD
	s_movk_i32 s0, 0x68
	v_and_b32_e32 v129, 0x80, v1
	v_mov_b32_e32 v1, 0
	v_mul_u32_u24_sdwa v0, v0, s0 dst_sel:DWORD dst_unused:UNUSED_PAD src0_sel:WORD_1 src1_sel:DWORD
	v_lshlrev_b32_e32 v12, 1, v146
	v_bfe_u32 v5, v128, 5, 1
	v_mul_u32_u24_e32 v11, 0x900, v190
	v_lshl_add_u32 v149, v0, 1, v12
	v_or_b32_e32 v0, 32, v7
	v_lshlrev_b32_e32 v16, 1, v3
	v_mov_b32_e32 v17, v1
	v_lshlrev_b32_e32 v136, 4, v5
	v_mul_u32_u24_e32 v141, 0x90, v7
	s_movk_i32 s1, 0x100
	s_movk_i32 s0, 0xd0
	v_mul_u32_u24_e32 v151, 0xd0, v7
	v_mul_u32_u24_e32 v7, 0x90, v0
	v_lshlrev_b32_e32 v0, 1, v11
	v_lshl_add_u64 v[16:17], s[86:87], 0, v[16:17]
	v_mov_b32_e32 v137, v1
	v_cmp_gt_u32_e64 s[4:5], s1, v128
	v_lshlrev_b32_e32 v150, 3, v9
	v_mul_u32_u24_sdwa v18, v13, s0 dst_sel:DWORD dst_unused:UNUSED_PAD src0_sel:WORD_1 src1_sel:DWORD
	v_lshlrev_b32_e32 v14, 4, v9
	v_lshl_add_u64 v[16:17], v[16:17], 0, v[136:137]
	s_mov_b64 s[0:1], 0x6bf1000
	v_mov_b32_e32 v9, v1
	v_lshl_add_u64 v[154:155], s[86:87], 0, v[0:1]
	v_and_b32_e32 v3, 7, v128
	s_add_u32 s8, s86, 0x3831000
	v_lshl_add_u64 v[152:153], v[16:17], 0, s[0:1]
	v_lshl_add_u64 v[8:9], v[154:155], 0, v[8:9]
	s_mov_b64 s[0:1], 0x4eb1000
	v_lshlrev_b32_e32 v160, 4, v3
	s_mov_b32 s6, 0x15555556
	s_addc_u32 s9, s87, 0
	v_lshl_add_u64 v[156:157], v[8:9], 0, s[0:1]
	s_mov_b64 s[0:1], 0xa1f1000
	s_movk_i32 s24, 0x600
	v_or_b32_e32 v166, v160, v0
	v_mul_hi_u32 v0, v128, s6
	v_mov_b32_e32 v13, v1
	s_add_u32 s10, s86, 0x4a31000
	v_lshl_add_u64 v[158:159], v[8:9], 0, s[0:1]
	v_lshlrev_b32_e32 v3, 5, v128
	v_mad_u64_u32 v[168:169], s[0:1], v0, s24, v[12:13]
	v_mbcnt_lo_u32_b32 v0, -1, 0
	v_lshlrev_b32_e32 v134, 3, v5
	s_addc_u32 s11, s87, 0
	v_and_b32_e32 v8, 0x7f00, v3
	v_add_u32_e32 v3, 0x200, v128
	v_mbcnt_hi_u32_b32 v199, -1, v0
	v_lshlrev_b32_e32 v6, 7, v190
	v_sub_u32_e32 v5, v136, v134
	v_add_u32_e32 v19, v134, v134
	s_add_u32 s12, s86, 0x86f1000
	v_mov_b32_e32 v9, v1
	v_mul_hi_u32 v3, v3, s6
	v_mov_b32_e32 v15, v1
	v_and_b32_e32 v0, 64, v199
	v_or_b32_e32 v135, 0x4000, v129
	s_movk_i32 s20, 0x900
	v_mul_u32_u24_e32 v147, 0x90, v196
	v_or_b32_e32 v140, 0x2000, v138
	v_or_b32_e32 v142, 0x4000, v138
	v_or_b32_e32 v144, 0x6000, v138
	s_addc_u32 s13, s87, 0
	s_lshl_b32 s21, s22, 1
	v_mov_b32_e32 v161, v1
	v_lshl_add_u64 v[162:163], s[86:87], 0, v[8:9]
	v_mad_u64_u32 v[164:165], s[0:1], v3, s24, v[14:15]
	v_mov_b32_e32 v167, v1
	v_lshlrev_b32_e32 v170, 1, v2
	v_lshlrev_b32_e32 v172, 1, v6
	s_mov_b32 s25, 0x48000
	v_add_u32_e32 v137, v136, v141
	s_mov_b32 s26, 0x41000000
	v_add_u32_e32 v197, v5, v141
	s_mov_b64 s[14:15], 0x100
	s_movk_i32 s27, 0xc0
	v_lshlrev_b32_e32 v174, 1, v10
	v_add_u32_e32 v198, v19, v151
	s_mov_b64 s[18:19], 0x30000
	v_lshlrev_b32_e32 v176, 1, v134
	v_lshlrev_b32_e32 v178, 1, v4
	v_xor_b32_e32 v200, 32, v199
	v_add_u32_e32 v201, 64, v0
	v_add_u32_e32 v202, v18, v14
	v_add_u32_e32 v203, v134, v7
	v_and_b32_e32 v253, 1, v128
	v_lshlrev_b32_e32 v253, 3, v253
	v_sub_u32_e32 v253, v139, v253
	s_branch .LBB0_540

.LBB0_706:
	s_or_b64 exec, exec, s[8:9]
	v_cvt_f32_u32_e32 v4, v2
	s_waitcnt vmcnt(0)
	v_readfirstlane_b32 s6, v3
	v_sub_u32_e32 v3, 0, v2
	v_rcp_iflag_f32_e32 v4, v4
	v_add_u32_e32 v5, s6, v1
	v_mul_f32_e32 v4, 0x4f7ffffe, v4
	v_cvt_u32_f32_e32 v4, v4
	v_mul_lo_u32 v1, v3, v4
	v_mul_hi_u32 v1, v4, v1
	v_add_u32_e32 v1, v4, v1
	v_mul_hi_u32 v1, v5, v1
	v_mul_lo_u32 v3, v1, v2
	v_sub_u32_e32 v3, v5, v3
	v_add_u32_e32 v4, 1, v1
	v_cmp_ge_u32_e32 vcc, v3, v2
	s_nop 1
	v_cndmask_b32_e32 v1, v1, v4, vcc
	v_sub_u32_e32 v4, v3, v2
	v_cndmask_b32_e32 v3, v3, v4, vcc
	v_add_u32_e32 v4, 1, v1
	v_cmp_ge_u32_e32 vcc, v3, v2
	v_add_u32_e32 v3, 1, v5
	s_nop 0
	v_cndmask_b32_e32 v1, v1, v4, vcc
	v_mul_lo_u32 v4, v2, v1
	v_add_u32_e32 v2, v4, v2
	v_cmp_ne_u32_e32 vcc, v3, v2
	s_and_saveexec_b64 s[6:7], vcc
	s_xor_b64 s[6:7], exec, s[6:7]
	s_cbranch_execz .LBB0_720
	s_waitcnt lgkmcnt(0)
	buffer_inv sc1
	v_mov_b32_e32 v1, v0
	v_mov_b32_e32 v0, 0
	s_add_u32 s12, s86, 0xe7b1040
	s_addc_u32 s13, s87, 0
	global_load_dword v0, v0, s[12:13] sc1
	s_waitcnt vmcnt(0)
	v_cmp_ne_u32_e32 vcc, v0, v1
	s_and_saveexec_b64 s[8:9], vcc
	s_cbranch_execz .LBB0_719
	s_add_u32 s10, s86, 0xe7b1200
	s_addc_u32 s11, s87, 0
	s_mov_b32 s26, 1
	s_mov_b64 s[14:15], 0
	v_mov_b32_e32 v0, 0
	s_branch .LBB0_710

.LBB0_720:
	s_andn2_saveexec_b64 s[6:7], s[6:7]
	s_cbranch_execz .LBB0_740
	s_mov_b64 s[6:7], exec
	buffer_wbl2 sc1
	buffer_inv sc1
	s_waitcnt lgkmcnt(0)
	s_waitcnt vmcnt(0)
	v_readfirstlane_b32 s99, v0
	s_add_u32 s100, s86, 0xe7b1040
	s_addc_u32 s101, s87, 0
	v_mov_b32_e32 v0, 0
	v_mov_b32_e32 v2, 1
	global_atomic_add v0, v2, s[100:101]
	s_mov_b32 s98, 0

.Lxb_done_4:
	s_waitcnt vmcnt(0)
.LBB0_740:
	s_or_b64 exec, exec, s[0:1]
	s_add_u32 s70, s86, 0x3031000
	s_addc_u32 s71, s87, 0
	s_cmpk_lt_i32 s2, 0x100
	s_cselect_b64 s[0:1], -1, 0
	v_writelane_b32 v252, s0, 50
	s_cmpk_gt_i32 s2, 0xff
	s_waitcnt lgkmcnt(0)
	s_barrier
	v_writelane_b32 v252, s1, 51
	s_cbranch_scc1 .LBB0_759
	v_and_b32_e32 v0, 0x78, v190
	v_add_u32_e32 v1, 64, v0
	v_or_b32_e32 v2, v1, v196
	v_or_b32_e32 v3, 0x80, v190
	v_add_u32_e32 v0, 0xc0, v0
	v_lshrrev_b32_e32 v7, 1, v2
	v_or_b32_e32 v4, v0, v196
	v_xor_b32_e32 v8, v7, v128
	v_lshrrev_b32_e32 v9, 1, v3
	v_lshlrev_b32_e32 v15, 2, v1
	v_lshlrev_b32_e32 v8, 4, v8
	v_xor_b32_e32 v10, v9, v128
	v_lshrrev_b32_e32 v11, 1, v4
	v_lshrrev_b32_e32 v13, 1, v128
	v_and_b32_e32 v15, 0x80, v15
	v_and_b32_e32 v7, 0x60, v7
	v_bitop3_b32 v1, v1, 31, v196 bitop3:0xc8
	v_lshlrev_b32_e32 v0, 2, v0
	v_and_b32_e32 v8, 0x70, v8
	v_lshlrev_b32_e32 v10, 4, v10
	v_xor_b32_e32 v12, v11, v128
	v_and_b32_e32 v13, 0x80, v13
	v_or3_b32 v1, v15, v7, v1
	v_and_b32_e32 v7, 0x60, v9
	v_and_b32_e32 v0, 0x80, v0
	v_and_b32_e32 v9, 0xe0, v11
	v_xor_b32_e32 v6, v188, v128
	v_and_b32_e32 v10, 0x70, v10
	v_lshlrev_b32_e32 v12, 4, v12
	v_or3_b32 v7, v13, v7, v193
	v_add_u32_e32 v9, v9, v0
	v_lshl_or_b32 v2, v2, 11, v8
	v_lshl_or_b32 v1, v1, 11, v8
	v_lshlrev_b32_e32 v6, 4, v6
	v_and_b32_e32 v12, 0x70, v12
	v_and_b32_e32 v14, 32, v188
	v_and_or_b32 v9, v4, 31, v9
	v_add_u32_e32 v138, 0xc3b1000, v2
	v_lshl_or_b32 v2, v3, 11, v10
	v_add_u32_e32 v146, 0x1db1000, v1
	v_lshl_or_b32 v1, v7, 11, v10
	v_and_b32_e32 v6, 0x70, v6
	v_or3_b32 v14, v14, v13, v193
	v_add_u32_e32 v140, 0xc3b1000, v2
	v_lshl_or_b32 v2, v4, 11, v12
	v_add_u32_e32 v148, 0x1db1000, v1
	v_lshl_or_b32 v1, v9, 11, v12
	v_add_u32_e32 v142, 0xc3b1000, v2
	v_lshl_or_b32 v2, v14, 11, v6
	v_add_u32_e32 v150, 0x1db1000, v1
	v_lshl_or_b32 v1, v130, 14, v133
	v_add_u32_e32 v144, 0x1db1000, v2
	v_or_b32_e32 v2, v1, v8
	v_or_b32_e32 v1, v1, v12
	v_lshlrev_b32_e32 v5, 11, v190
	v_add_u32_e32 v156, 0xc411000, v1
	v_mov_b32_e32 v1, 0x78
	v_add_u32_e32 v152, 0xc3d1000, v2
	v_or_b32_e32 v2, v5, v10
	v_bitop3_b32 v1, v190, 7, v1 bitop3:0xe0
	v_add_u32_e32 v154, 0xc3f1000, v2
	v_add_u32_e32 v2, 64, v1
	v_add_u32_e32 v1, 0xc0, v1
	v_lshlrev_b16_e32 v3, 3, v130
	v_lshrrev_b32_e32 v1, 1, v1
	v_lshrrev_b32_e32 v2, 1, v2
	v_bitop3_b16 v3, v3, v190, 7 bitop3:0xf8
	v_and_b32_e32 v1, 0xe0, v1
	s_add_u32 s0, s86, 0x1902000
	v_and_b32_e32 v2, 0x60, v2
	v_and_b32_e32 v3, 31, v3
	v_add_u32_e32 v0, v0, v1
	v_bitop3_b32 v11, v188, v191, 3 bitop3:0x6c
	s_addc_u32 s1, s87, 0
	v_or3_b32 v2, v15, v2, v3
	v_or_b32_e32 v0, v0, v3
	v_lshlrev_b32_e32 v129, 4, v11
	v_or_b32_e32 v11, v5, v6
	s_add_u32 s6, s86, 0x80
	v_lshl_or_b32 v2, v2, 11, v8
	v_lshl_or_b32 v0, v0, 11, v12
	v_lshlrev_b32_e32 v135, 4, v192
	v_add_u32_e32 v134, 0xc3b1000, v11
	v_mov_b32_e32 v137, 0
	s_addc_u32 s7, s87, 0
	v_add_u32_e32 v158, 0x1db1000, v2
	v_add_u32_e32 v160, 0x1db1000, v0
	s_mov_b32 s12, 0x8000
	v_mov_b32_e32 v139, 0x8000
	s_mov_b32 s13, 0x10000
	s_mov_b32 s14, 0x12000
	s_movk_i32 s15, 0x3fff
	s_mov_b32 s16, 0x18000
	s_mov_b32 s17, s2

.LBB0_892:
	s_or_b64 exec, exec, s[8:9]
	v_cvt_f32_u32_e32 v4, v2
	s_waitcnt vmcnt(0)
	v_readfirstlane_b32 s6, v3
	v_sub_u32_e32 v3, 0, v2
	v_rcp_iflag_f32_e32 v4, v4
	v_add_u32_e32 v5, s6, v1
	v_mul_f32_e32 v4, 0x4f7ffffe, v4
	v_cvt_u32_f32_e32 v4, v4
	v_mul_lo_u32 v1, v3, v4
	v_mul_hi_u32 v1, v4, v1
	v_add_u32_e32 v1, v4, v1
	v_mul_hi_u32 v1, v5, v1
	v_mul_lo_u32 v3, v1, v2
	v_sub_u32_e32 v3, v5, v3
	v_add_u32_e32 v4, 1, v1
	v_cmp_ge_u32_e32 vcc, v3, v2
	s_nop 1
	v_cndmask_b32_e32 v1, v1, v4, vcc
	v_sub_u32_e32 v4, v3, v2
	v_cndmask_b32_e32 v3, v3, v4, vcc
	v_add_u32_e32 v4, 1, v1
	v_cmp_ge_u32_e32 vcc, v3, v2
	v_add_u32_e32 v3, 1, v5
	s_nop 0
	v_cndmask_b32_e32 v1, v1, v4, vcc
	v_mul_lo_u32 v4, v2, v1
	v_add_u32_e32 v2, v4, v2
	v_cmp_ne_u32_e32 vcc, v3, v2
	s_and_saveexec_b64 s[6:7], vcc
	s_xor_b64 s[6:7], exec, s[6:7]
	s_cbranch_execz .LBB0_906
	s_waitcnt lgkmcnt(0)
	buffer_inv sc1
	v_mov_b32_e32 v1, v0
	v_mov_b32_e32 v0, 0
	s_add_u32 s12, s86, 0xe7b1050
	s_addc_u32 s13, s87, 0
	global_load_dword v0, v0, s[12:13] sc1
	s_waitcnt vmcnt(0)
	v_cmp_ne_u32_e32 vcc, v0, v1
	s_and_saveexec_b64 s[8:9], vcc
	s_cbranch_execz .LBB0_905
	s_add_u32 s10, s86, 0xe7b1200
	s_addc_u32 s11, s87, 0
	s_mov_b32 s30, 1
	s_mov_b64 s[14:15], 0
	v_mov_b32_e32 v0, 0
	s_branch .LBB0_896

.LBB0_900:
	global_load_dword v2, v0, s[12:13] sc1
	s_add_i32 s30, s30, 1
	s_mov_b64 s[26:27], -1
	s_waitcnt vmcnt(0)
	v_cmp_eq_u32_e32 vcc, v2, v1
	s_orn2_b64 s[24:25], vcc, exec
	s_branch .LBB0_895

.LBB0_906:
	s_andn2_saveexec_b64 s[6:7], s[6:7]
	s_cbranch_execz .LBB0_926
	s_mov_b64 s[6:7], exec
	buffer_wbl2 sc1
	buffer_inv sc1
	s_waitcnt lgkmcnt(0)
	s_waitcnt vmcnt(0)
	v_readfirstlane_b32 s99, v0
	s_add_u32 s100, s86, 0xe7b1050
	s_addc_u32 s101, s87, 0
	v_mov_b32_e32 v0, 0
	v_mov_b32_e32 v2, 1
	global_atomic_add v0, v2, s[100:101]
	s_mov_b32 s98, 0

.Lxb_done_5:
	s_waitcnt vmcnt(0)
.LBB0_926:
	s_or_b64 exec, exec, s[0:1]
	s_waitcnt lgkmcnt(0)
	s_barrier
	s_mov_b64 s[0:1], exec
	v_readlane_b32 s4, v252, 38
	v_readlane_b32 s5, v252, 39
	s_and_b64 s[4:5], s[0:1], s[4:5]
	s_mov_b64 exec, s[4:5]
	s_cbranch_execz .LBB0_937
	v_mbcnt_lo_u32_b32 v1, -1, 0
	v_mbcnt_hi_u32_b32 v1, -1, v1
	v_and_b32_e32 v2, 64, v1
	v_add_u32_e32 v2, 64, v2
	v_xor_b32_e32 v3, 32, v1
	v_cmp_lt_i32_e32 vcc, v3, v2
	v_lshlrev_b32_e32 v0, 2, v128
	v_and_b32_e32 v0, 0xfc, v0
	v_cndmask_b32_e32 v3, v1, v3, vcc
	v_lshlrev_b32_e32 v40, 2, v3
	v_xor_b32_e32 v3, 16, v1
	v_cmp_lt_i32_e32 vcc, v3, v2
	v_mov_b32_e32 v21, 0
	v_lshlrev_b32_e32 v20, 2, v0
	v_cndmask_b32_e32 v3, v1, v3, vcc
	v_lshlrev_b32_e32 v41, 2, v3
	v_xor_b32_e32 v3, 8, v1
	v_cmp_lt_i32_e32 vcc, v3, v2
	s_add_u32 s4, s86, 0x1903000
	v_lshl_add_u64 v[22:23], s[66:67], 0, v[20:21]
	v_cndmask_b32_e32 v3, v1, v3, vcc
	v_lshlrev_b32_e32 v42, 2, v3
	v_xor_b32_e32 v3, 4, v1
	v_cmp_lt_i32_e32 vcc, v3, v2
	v_or_b32_e32 v4, 0x200, v0
	v_or_b32_e32 v6, 0x300, v0
	v_cndmask_b32_e32 v3, v1, v3, vcc
	v_lshlrev_b32_e32 v43, 2, v3
	v_xor_b32_e32 v3, 2, v1
	v_cmp_lt_i32_e32 vcc, v3, v2
	v_lshlrev_b32_e32 v20, 1, v0
	s_addc_u32 s5, s87, 0
	v_cndmask_b32_e32 v3, v1, v3, vcc
	v_lshlrev_b32_e32 v44, 2, v3
	v_xor_b32_e32 v3, 1, v1
	v_cmp_lt_i32_e32 vcc, v3, v2
	v_or_b32_e32 v2, 0x100, v0
	s_lshl_b32 s12, s22, 4
	v_cndmask_b32_e32 v1, v1, v3, vcc
	v_lshlrev_b32_e32 v45, 2, v1
	v_lshl_add_u64 v[24:25], s[88:89], 0, v[20:21]
	s_mov_b64 s[6:7], 0
	s_movk_i32 s13, 0x3fff
	v_lshlrev_b32_e32 v26, 2, v0
	v_mov_b32_e32 v27, v21
	v_mov_b32_e32 v46, 0x358637bd
	s_mov_b32 s14, 0x800000
	s_mov_b64 s[8:9], 0x1000
	v_lshlrev_b32_e32 v28, 2, v2
	v_mov_b32_e32 v29, v21
	v_lshlrev_b32_e32 v30, 2, v4
	v_mov_b32_e32 v31, v21
	v_lshlrev_b32_e32 v32, 2, v6
	v_mov_b32_e32 v33, v21
	s_movk_i32 s15, 0x47ff
	v_mov_b32_e32 v34, v132
	s_branch .LBB0_929

.LBB0_955:
	s_or_b64 exec, exec, s[8:9]
	v_cvt_f32_u32_e32 v4, v2
	s_waitcnt vmcnt(0)
	v_readfirstlane_b32 s6, v3
	v_sub_u32_e32 v3, 0, v2
	v_rcp_iflag_f32_e32 v4, v4
	v_add_u32_e32 v5, s6, v1
	v_mul_f32_e32 v4, 0x4f7ffffe, v4
	v_cvt_u32_f32_e32 v4, v4
	v_mul_lo_u32 v1, v3, v4
	v_mul_hi_u32 v1, v4, v1
	v_add_u32_e32 v1, v4, v1
	v_mul_hi_u32 v1, v5, v1
	v_mul_lo_u32 v3, v1, v2
	v_sub_u32_e32 v3, v5, v3
	v_add_u32_e32 v4, 1, v1
	v_cmp_ge_u32_e32 vcc, v3, v2
	s_nop 1
	v_cndmask_b32_e32 v1, v1, v4, vcc
	v_sub_u32_e32 v4, v3, v2
	v_cndmask_b32_e32 v3, v3, v4, vcc
	v_add_u32_e32 v4, 1, v1
	v_cmp_ge_u32_e32 vcc, v3, v2
	v_add_u32_e32 v3, 1, v5
	s_nop 0
	v_cndmask_b32_e32 v1, v1, v4, vcc
	v_mul_lo_u32 v4, v2, v1
	v_add_u32_e32 v2, v4, v2
	v_cmp_ne_u32_e32 vcc, v3, v2
	s_and_saveexec_b64 s[6:7], vcc
	s_xor_b64 s[6:7], exec, s[6:7]
	s_cbranch_execz .LBB0_969
	s_waitcnt lgkmcnt(0)
	buffer_inv sc1
	v_mov_b32_e32 v1, v0
	v_mov_b32_e32 v0, 0
	s_add_u32 s12, s86, 0xe7b1060
	s_addc_u32 s13, s87, 0
	global_load_dword v0, v0, s[12:13] sc1
	s_waitcnt vmcnt(0)
	v_cmp_ne_u32_e32 vcc, v0, v1
	s_and_saveexec_b64 s[8:9], vcc
	s_cbranch_execz .LBB0_968
	s_add_u32 s10, s86, 0xe7b1200
	s_addc_u32 s11, s87, 0
	s_mov_b32 s30, 1
	s_mov_b64 s[14:15], 0
	v_mov_b32_e32 v0, 0
	s_branch .LBB0_959

.LBB0_969:
	s_andn2_saveexec_b64 s[6:7], s[6:7]
	s_cbranch_execz .LBB0_989
	s_mov_b64 s[6:7], exec
	buffer_wbl2 sc1
	buffer_inv sc1
	s_waitcnt lgkmcnt(0)
	s_waitcnt vmcnt(0)
	v_readfirstlane_b32 s99, v0
	s_add_u32 s100, s86, 0xe7b1060
	s_addc_u32 s101, s87, 0
	v_mov_b32_e32 v0, 0
	v_mov_b32_e32 v2, 1
	global_atomic_add v0, v2, s[100:101]
	s_mov_b32 s98, 0

.Lxb_done_6:
	s_waitcnt vmcnt(0)
.LBB0_989:
	s_or_b64 exec, exec, s[0:1]
	s_add_u32 s92, s86, 0x196f000
	s_add_u32 s52, s86, 0x3831000
	s_addc_u32 s53, s87, 0
	s_cmpk_gt_i32 s2, 0x6df
	s_waitcnt lgkmcnt(0)
	s_barrier
	s_cbranch_scc1 .LBB0_1036
	v_and_b32_e32 v0, 0x78, v190
	v_add_u32_e32 v4, 64, v0
	v_add_u32_e32 v6, 0xc0, v0
	v_xor_b32_e32 v0, v188, v128
	v_or_b32_e32 v5, v4, v196
	v_lshlrev_b32_e32 v0, 4, v0
	s_movk_i32 s0, 0x7f
	v_and_b32_e32 v134, 0x70, v0
	v_bitop3_b32 v0, v4, s0, v196 bitop3:0xc8
	v_lshrrev_b32_e32 v8, 1, v5
	v_add_u32_e32 v138, -1, v0
	v_xor_b32_e32 v0, v8, v128
	v_mov_b32_e32 v135, 0
	v_lshlrev_b32_e32 v0, 4, v0
	v_and_b32_e32 v0, 0x70, v0
	v_mov_b32_e32 v1, v135
	v_or_b32_e32 v7, v6, v196
	v_lshl_add_u64 v[140:141], s[88:89], 0, v[0:1]
	v_bitop3_b32 v1, v6, s0, v196 bitop3:0xc8
	v_lshrrev_b32_e32 v139, 7, v6
	v_add_u32_e32 v142, -1, v1
	v_lshrrev_b32_e32 v1, 1, v7
	v_lshlrev_b32_e32 v6, 2, v6
	v_xor_b32_e32 v2, v1, v128
	v_and_b32_e32 v6, 0x80, v6
	v_and_b32_e32 v1, 0xe0, v1
	v_lshlrev_b32_e32 v2, 4, v2
	v_add_u32_e32 v1, v1, v6
	v_readlane_b32 s4, v252, 0
	v_and_b32_e32 v2, 0x70, v2
	v_mov_b32_e32 v3, v135
	v_and_or_b32 v1, v7, 31, v1
	v_readlane_b32 s6, v252, 2
	v_readlane_b32 s8, v252, 4
	v_lshl_add_u64 v[136:137], s[88:89], 0, v[134:135]
	v_lshl_add_u64 v[144:145], s[88:89], 0, v[2:3]
	v_lshrrev_b32_e32 v3, 1, v128
	v_readlane_b32 s7, v252, 3
	v_readlane_b32 s9, v252, 5
	s_add_u32 s8, s6, 0x2c00
	v_lshl_or_b32 v1, v1, 11, v2
	v_lshrrev_b32_e32 v137, 7, v4
	s_movk_i32 s0, 0x80
	v_and_b32_e32 v3, 0x80, v3
	v_and_b32_e32 v9, 32, v188
	v_lshlrev_b32_e32 v4, 2, v4
	v_and_b32_e32 v8, 0x60, v8
	v_readlane_b32 s10, v252, 6
	s_addc_u32 s9, s7, 0
	v_add_u32_e32 v152, 0x1fb1000, v1
	v_lshlrev_b16_e32 v1, 3, v130
	v_or3_b32 v10, v9, v3, v193
	v_and_or_b32 v4, v4, s0, v8
	v_or3_b32 v3, v9, v193, v3
	v_bitop3_b32 v6, v188, v191, 3 bitop3:0x6c
	v_readlane_b32 s11, v252, 7
	s_add_u32 s10, s6, 0x5800
	v_bitop3_b16 v1, v1, v190, 7 bitop3:0xf8
	v_and_or_b32 v5, v5, 31, v4
	v_lshlrev_b32_e32 v3, 11, v3
	v_lshlrev_b32_e32 v141, 4, v6
	s_addc_u32 s11, s7, 0
	v_or_b32_e32 v6, 0x1fb1000, v134
	s_mov_b32 s0, 0x20000
	v_and_or_b32 v1, v1, 31, v4
	v_readlane_b32 s12, v252, 8
	v_readlane_b32 s13, v252, 9
	v_readlane_b32 s14, v252, 10
	v_readlane_b32 s15, v252, 11
	v_readlane_b32 s16, v252, 12
	v_readlane_b32 s17, v252, 13
	v_lshl_or_b32 v5, v5, 11, v0
	v_add3_u32 v150, v6, v3, s0
	s_add_u32 s56, s86, 0x80
	v_lshl_or_b32 v134, v1, 11, v0
	s_mov_b64 s[0:1], 0x1fb1000
	v_add_u32_e32 v129, -1, v190
	v_lshlrev_b32_e32 v143, 4, v192
	v_lshl_add_u32 v146, v10, 11, v6
	v_add_u32_e32 v148, 0x1fb1000, v5
	s_addc_u32 s57, s87, 0
	v_lshl_add_u64 v[154:155], v[134:135], 0, s[0:1]
	s_mov_b32 s12, 0xaaaaaaab
	s_movk_i32 s13, 0x87
	s_mov_b32 s14, 0x78787879
	s_movk_i32 s15, 0x7e
	v_mov_b32_e32 v145, s92
	v_mov_b32_e32 v147, 0x8000
	s_movk_i32 s16, 0x1600
	v_mov_b32_e32 v149, 0x4000
	v_mov_b32_e32 v151, 3
	v_mov_b32_e32 v153, 7
	s_mov_b32 s17, s2
	v_readlane_b32 s5, v252, 1
	v_readlane_b32 s18, v252, 14
	v_readlane_b32 s19, v252, 15
	s_branch .LBB0_992

.LBB0_1155:
	s_or_b64 exec, exec, s[8:9]
	v_cvt_f32_u32_e32 v4, v2
	s_waitcnt vmcnt(0)
	v_readfirstlane_b32 s6, v3
	v_sub_u32_e32 v3, 0, v2
	v_rcp_iflag_f32_e32 v4, v4
	v_add_u32_e32 v5, s6, v1
	v_mul_f32_e32 v4, 0x4f7ffffe, v4
	v_cvt_u32_f32_e32 v4, v4
	v_mul_lo_u32 v1, v3, v4
	v_mul_hi_u32 v1, v4, v1
	v_add_u32_e32 v1, v4, v1
	v_mul_hi_u32 v1, v5, v1
	v_mul_lo_u32 v3, v1, v2
	v_sub_u32_e32 v3, v5, v3
	v_add_u32_e32 v4, 1, v1
	v_cmp_ge_u32_e32 vcc, v3, v2
	s_nop 1
	v_cndmask_b32_e32 v1, v1, v4, vcc
	v_sub_u32_e32 v4, v3, v2
	v_cndmask_b32_e32 v3, v3, v4, vcc
	v_add_u32_e32 v4, 1, v1
	v_cmp_ge_u32_e32 vcc, v3, v2
	v_add_u32_e32 v3, 1, v5
	s_nop 0
	v_cndmask_b32_e32 v1, v1, v4, vcc
	v_mul_lo_u32 v4, v2, v1
	v_add_u32_e32 v2, v4, v2
	v_cmp_ne_u32_e32 vcc, v3, v2
	s_and_saveexec_b64 s[6:7], vcc
	s_xor_b64 s[6:7], exec, s[6:7]
	s_cbranch_execz .LBB0_1169
	s_waitcnt lgkmcnt(0)
	buffer_inv sc1
	v_mov_b32_e32 v1, v0
	v_mov_b32_e32 v0, 0
	s_add_u32 s12, s86, 0xe7b1070
	s_addc_u32 s13, s87, 0
	global_load_dword v0, v0, s[12:13] sc1
	s_waitcnt vmcnt(0)
	v_cmp_ne_u32_e32 vcc, v0, v1
	s_and_saveexec_b64 s[8:9], vcc
	s_cbranch_execz .LBB0_1168
	s_add_u32 s10, s86, 0xe7b1200
	s_addc_u32 s11, s87, 0
	s_mov_b32 s30, 1
	s_mov_b64 s[14:15], 0
	v_mov_b32_e32 v0, 0
	s_branch .LBB0_1159

.LBB0_1169:
	s_andn2_saveexec_b64 s[6:7], s[6:7]
	s_cbranch_execz .LBB0_1189
	s_mov_b64 s[6:7], exec
	buffer_wbl2 sc1
	buffer_inv sc1
	s_waitcnt lgkmcnt(0)
	s_waitcnt vmcnt(0)
	v_readfirstlane_b32 s99, v0
	s_add_u32 s100, s86, 0xe7b1070
	s_addc_u32 s101, s87, 0
	v_mov_b32_e32 v0, 0
	v_mov_b32_e32 v2, 1
	global_atomic_add v0, v2, s[100:101]
	s_mov_b32 s98, 0

.Lxb_done_7:
	s_waitcnt vmcnt(0)
.LBB0_1189:
	s_or_b64 exec, exec, s[0:1]
	v_readlane_b32 s4, v252, 50
	v_readlane_b32 s5, v252, 51
	s_ashr_i32 s51, s22, 31
	s_andn2_b64 vcc, exec, s[4:5]
	s_waitcnt lgkmcnt(0)
	v_cndmask_b32_e64 v0, 0, 1, s[4:5]
	v_cmp_ne_u32_e64 s[0:1], 1, v0
	s_barrier
	s_nop 0
	v_writelane_b32 v252, s0, 32
	s_nop 1
	v_writelane_b32 v252, s1, 33
	s_cbranch_vccnz .LBB0_1208
	v_and_b32_e32 v0, 0x78, v190
	v_add_u32_e32 v1, 64, v0
	v_add_u32_e32 v0, 0xc0, v0
	v_or_b32_e32 v2, v1, v196
	v_or_b32_e32 v3, v0, v196
	s_waitcnt vmcnt(2)
	v_lshrrev_b32_e32 v5, 1, v2
	v_lshrrev_b32_e32 v7, 1, v3
	v_xor_b32_e32 v6, v5, v128
	v_xor_b32_e32 v8, v7, v128
	v_lshlrev_b32_e32 v10, 2, v1
	v_lshlrev_b32_e32 v6, 4, v6
	v_lshlrev_b32_e32 v8, 3, v8
	v_and_b32_e32 v10, 0x80, v10
	v_and_b32_e32 v5, 0x60, v5
	v_bitop3_b32 v1, v1, 31, v196 bitop3:0xc8
	v_lshlrev_b32_e32 v0, 2, v0
	v_and_b32_e32 v6, 0x70, v6
	v_and_b32_e32 v134, 56, v8
	v_lshrrev_b32_e32 v8, 1, v128
	s_movk_i32 s0, 0x60
	v_or3_b32 v1, v10, v5, v1
	v_and_b32_e32 v0, 0x80, v0
	v_and_b32_e32 v7, 0xe0, v7
	v_mul_u32_u24_e32 v2, 0x1600, v2
	v_xor_b32_e32 v4, v188, v128
	v_and_b32_e32 v8, 0x80, v8
	v_and_b32_e32 v9, 32, v188
	v_bitop3_b32 v5, v188, s0, 64 bitop3:0xc8
	v_add_u32_e32 v0, v7, v0
	v_or_b32_e32 v2, v2, v6
	v_mul_u32_u24_e32 v1, 0x1600, v1
	v_lshlrev_b32_e32 v4, 4, v4
	v_or3_b32 v9, v9, v8, v193
	v_or3_b32 v5, v8, v5, v193
	v_and_or_b32 v0, v3, 31, v0
	v_bitop3_b32 v7, v188, v191, 3 bitop3:0x6c
	s_add_u32 s0, s86, 0x1905000
	s_movk_i32 s6, 0x1600
	v_add_u32_e32 v140, 0x3831000, v2
	v_mov_b32_e32 v2, 0x3831000
	v_or_b32_e32 v1, v1, v6
	v_and_b32_e32 v4, 0x70, v4
	v_lshlrev_b32_e32 v129, 4, v7
	s_addc_u32 s1, s87, 0
	v_mul_u32_u24_e32 v7, 0x1600, v190
	v_mad_u32_u24 v144, v3, s6, v2
	v_mul_u32_u24_e32 v2, 0x1600, v9
	v_add_u32_e32 v148, 0x2ab1000, v1
	v_mul_u32_u24_e32 v1, 0x1600, v5
	v_mul_u32_u24_e32 v0, 0x1600, v0
	v_or_b32_e32 v7, v7, v4
	v_or_b32_e32 v2, v2, v4
	v_or_b32_e32 v1, v1, v4
	v_lshl_or_b32 v0, v134, 1, v0
	s_add_u32 s8, s86, 0x80
	v_mov_b32_e32 v137, 0
	v_lshlrev_b32_e32 v135, 4, v192
	v_add_u32_e32 v138, 0x3831000, v7
	v_add_u32_e32 v142, 0x38e1000, v7
	v_add_u32_e32 v146, 0x2ab1000, v2
	v_add_u32_e32 v150, 0x2ab1000, v1
	v_add_u32_e32 v152, 0x2ab1000, v0
	s_addc_u32 s9, s87, 0
	s_mov_b32 s14, 0x8000
	v_mov_b32_e32 v139, 0x8000
	s_mov_b32 s15, 0x10000
	s_mov_b32 s16, 0x18000
	s_mov_b32 s17, s2

.LBB0_1357:
	s_or_b64 exec, exec, s[10:11]
	v_cvt_f32_u32_e32 v4, v2
	s_waitcnt vmcnt(0)
	v_readfirstlane_b32 s8, v3
	v_sub_u32_e32 v3, 0, v2
	v_rcp_iflag_f32_e32 v4, v4
	v_add_u32_e32 v5, s8, v1
	v_mul_f32_e32 v4, 0x4f7ffffe, v4
	v_cvt_u32_f32_e32 v4, v4
	v_mul_lo_u32 v1, v3, v4
	v_mul_hi_u32 v1, v4, v1
	v_add_u32_e32 v1, v4, v1
	v_mul_hi_u32 v1, v5, v1
	v_mul_lo_u32 v3, v1, v2
	v_sub_u32_e32 v3, v5, v3
	v_add_u32_e32 v4, 1, v1
	v_cmp_ge_u32_e32 vcc, v3, v2
	s_nop 1
	v_cndmask_b32_e32 v1, v1, v4, vcc
	v_sub_u32_e32 v4, v3, v2
	v_cndmask_b32_e32 v3, v3, v4, vcc
	v_add_u32_e32 v4, 1, v1
	v_cmp_ge_u32_e32 vcc, v3, v2
	v_add_u32_e32 v3, 1, v5
	s_nop 0
	v_cndmask_b32_e32 v1, v1, v4, vcc
	v_mul_lo_u32 v4, v2, v1
	v_add_u32_e32 v2, v4, v2
	v_cmp_ne_u32_e32 vcc, v3, v2
	s_and_saveexec_b64 s[8:9], vcc
	s_xor_b64 s[8:9], exec, s[8:9]
	s_cbranch_execz .LBB0_1371
	s_waitcnt lgkmcnt(0)
	buffer_inv sc1
	v_mov_b32_e32 v1, v0
	v_mov_b32_e32 v0, 0
	s_add_u32 s14, s86, 0xe7b1080
	s_addc_u32 s15, s87, 0
	global_load_dword v0, v0, s[14:15] sc1
	s_waitcnt vmcnt(0)
	v_cmp_ne_u32_e32 vcc, v0, v1
	s_and_saveexec_b64 s[10:11], vcc
	s_cbranch_execz .LBB0_1370
	s_add_u32 s12, s86, 0xe7b1200
	s_addc_u32 s13, s87, 0
	s_mov_b32 s28, 1
	s_mov_b64 s[16:17], 0
	v_mov_b32_e32 v0, 0
	s_branch .LBB0_1361

.LBB0_1371:
	s_andn2_saveexec_b64 s[8:9], s[8:9]
	s_cbranch_execz .LBB0_1391
	s_mov_b64 s[8:9], exec
	buffer_wbl2 sc1
	buffer_inv sc1
	s_waitcnt lgkmcnt(0)
	s_waitcnt vmcnt(0)
	v_readfirstlane_b32 s99, v0
	s_add_u32 s100, s86, 0xe7b1080
	s_addc_u32 s101, s87, 0
	v_mov_b32_e32 v0, 0
	v_mov_b32_e32 v2, 1
	global_atomic_add v0, v2, s[100:101]
	s_mov_b32 s98, 0

.Lxb_done_8:
	s_waitcnt vmcnt(0)
.LBB0_1391:
	s_or_b64 exec, exec, s[0:1]
	s_waitcnt lgkmcnt(0)
	s_barrier
	s_mov_b64 s[0:1], exec
	v_readlane_b32 s6, v252, 38
	v_readlane_b32 s7, v252, 39
	s_and_b64 s[6:7], s[0:1], s[6:7]
	s_mov_b64 exec, s[6:7]
	s_cbranch_execz .LBB0_1402
	v_mbcnt_lo_u32_b32 v1, -1, 0
	v_mbcnt_hi_u32_b32 v1, -1, v1
	v_and_b32_e32 v2, 64, v1
	v_add_u32_e32 v2, 64, v2
	v_xor_b32_e32 v3, 32, v1
	v_cmp_lt_i32_e32 vcc, v3, v2
	s_add_u32 s6, s86, 0x1936000
	s_addc_u32 s7, s87, 0
	v_cndmask_b32_e32 v3, v1, v3, vcc
	v_lshlrev_b32_e32 v46, 2, v3
	v_xor_b32_e32 v3, 16, v1
	v_cmp_lt_i32_e32 vcc, v3, v2
	v_lshlrev_b32_e32 v0, 2, v128
	s_add_u32 s10, s64, 0x1000
	v_cndmask_b32_e32 v3, v1, v3, vcc
	v_lshlrev_b32_e32 v47, 2, v3
	v_xor_b32_e32 v3, 8, v1
	v_cmp_lt_i32_e32 vcc, v3, v2
	v_and_b32_e32 v0, 0xfc, v0
	s_addc_u32 s11, s65, 0
	v_cndmask_b32_e32 v3, v1, v3, vcc
	v_lshlrev_b32_e32 v48, 2, v3
	v_xor_b32_e32 v3, 4, v1
	v_cmp_lt_i32_e32 vcc, v3, v2
	s_waitcnt vmcnt(5)
	v_mov_b32_e32 v21, 0
	v_lshlrev_b32_e32 v20, 2, v0
	v_cndmask_b32_e32 v3, v1, v3, vcc
	v_lshlrev_b32_e32 v49, 2, v3
	v_xor_b32_e32 v3, 2, v1
	v_cmp_lt_i32_e32 vcc, v3, v2
	v_lshl_add_u64 v[22:23], s[10:11], 0, v[20:21]
	s_waitcnt vmcnt(2)
	v_or_b32_e32 v4, 0x200, v0
	v_cndmask_b32_e32 v3, v1, v3, vcc
	v_lshlrev_b32_e32 v50, 2, v3
	v_xor_b32_e32 v3, 1, v1
	v_cmp_lt_i32_e32 vcc, v3, v2
	v_or_b32_e32 v2, 0x100, v0
	v_lshlrev_b32_e32 v20, 2, v2
	v_lshl_add_u64 v[24:25], s[10:11], 0, v[20:21]
	v_lshlrev_b32_e32 v20, 2, v4
	v_or_b32_e32 v6, 0x300, v0
	v_lshl_add_u64 v[26:27], s[10:11], 0, v[20:21]
	v_lshlrev_b32_e32 v20, 2, v6
	v_cndmask_b32_e32 v1, v1, v3, vcc
	s_waitcnt vmcnt(1)
	v_lshl_add_u64 v[28:29], s[10:11], 0, v[20:21]
	v_lshlrev_b32_e32 v20, 1, v0
	s_mov_b64 s[8:9], 0x1000
	v_lshlrev_b32_e32 v51, 2, v1
	s_lshl_b32 s14, s22, 4
	v_lshl_add_u64 v[30:31], s[88:89], 0, v[20:21]
	s_mov_b64 s[10:11], 0
	s_movk_i32 s15, 0x3fff
	v_lshlrev_b32_e32 v32, 2, v0
	v_mov_b32_e32 v33, v21
	v_mov_b32_e32 v52, 0x358637bd
	s_mov_b32 s16, 0x800000
	v_lshlrev_b32_e32 v34, 2, v2
	v_mov_b32_e32 v35, v21
	v_lshlrev_b32_e32 v36, 2, v4
	v_mov_b32_e32 v37, v21
	v_lshlrev_b32_e32 v38, 2, v6
	v_mov_b32_e32 v39, v21
	s_movk_i32 s17, 0x47ff
	v_mov_b32_e32 v40, v132
	s_branch .LBB0_1394

.LBB0_1420:
	s_or_b64 exec, exec, s[10:11]
	v_cvt_f32_u32_e32 v4, v2
	s_waitcnt vmcnt(0)
	v_readfirstlane_b32 s8, v3
	v_sub_u32_e32 v3, 0, v2
	v_rcp_iflag_f32_e32 v4, v4
	v_add_u32_e32 v5, s8, v1
	v_mul_f32_e32 v4, 0x4f7ffffe, v4
	v_cvt_u32_f32_e32 v4, v4
	v_mul_lo_u32 v1, v3, v4
	v_mul_hi_u32 v1, v4, v1
	v_add_u32_e32 v1, v4, v1
	v_mul_hi_u32 v1, v5, v1
	v_mul_lo_u32 v3, v1, v2
	v_sub_u32_e32 v3, v5, v3
	v_add_u32_e32 v4, 1, v1
	v_cmp_ge_u32_e32 vcc, v3, v2
	s_nop 1
	v_cndmask_b32_e32 v1, v1, v4, vcc
	v_sub_u32_e32 v4, v3, v2
	v_cndmask_b32_e32 v3, v3, v4, vcc
	v_add_u32_e32 v4, 1, v1
	v_cmp_ge_u32_e32 vcc, v3, v2
	v_add_u32_e32 v3, 1, v5
	s_nop 0
	v_cndmask_b32_e32 v1, v1, v4, vcc
	v_mul_lo_u32 v4, v2, v1
	v_add_u32_e32 v2, v4, v2
	v_cmp_ne_u32_e32 vcc, v3, v2
	s_and_saveexec_b64 s[8:9], vcc
	s_xor_b64 s[8:9], exec, s[8:9]
	s_cbranch_execz .LBB0_1434
	s_waitcnt lgkmcnt(0)
	buffer_inv sc1
	v_mov_b32_e32 v1, v0
	v_mov_b32_e32 v0, 0
	s_add_u32 s14, s86, 0xe7b1090
	s_addc_u32 s15, s87, 0
	global_load_dword v0, v0, s[14:15] sc1
	s_waitcnt vmcnt(0)
	v_cmp_ne_u32_e32 vcc, v0, v1
	s_and_saveexec_b64 s[10:11], vcc
	s_cbranch_execz .LBB0_1433
	s_add_u32 s12, s86, 0xe7b1200
	s_addc_u32 s13, s87, 0
	s_mov_b32 s28, 1
	s_mov_b64 s[16:17], 0
	v_mov_b32_e32 v0, 0
	s_branch .LBB0_1424

.LBB0_1434:
	s_andn2_saveexec_b64 s[8:9], s[8:9]
	s_cbranch_execz .LBB0_1454
	s_mov_b64 s[8:9], exec
	buffer_wbl2 sc1
	buffer_inv sc1
	s_waitcnt lgkmcnt(0)
	s_waitcnt vmcnt(0)
	v_readfirstlane_b32 s99, v0
	s_add_u32 s100, s86, 0xe7b1090
	s_addc_u32 s101, s87, 0
	v_mov_b32_e32 v0, 0
	v_mov_b32_e32 v2, 1
	global_atomic_add v0, v2, s[100:101]
	s_mov_b32 s98, 0

.Lxb_done_9:
	s_waitcnt vmcnt(0)
.LBB0_1454:
	s_or_b64 exec, exec, s[0:1]
	s_mul_hi_u32 s0, s33, 0x340
	s_mul_i32 s1, s0, s50
	s_sub_i32 s1, 0x340, s1
	s_add_i32 s6, s0, 1
	s_sub_i32 s7, s1, s50
	s_cmp_ge_u32 s1, s50
	s_cselect_b32 s0, s6, s0
	s_cselect_b32 s1, s7, s1
	s_add_i32 s6, s0, 1
	s_cmp_ge_u32 s1, s50
	s_cselect_b32 s0, s6, s0
	s_waitcnt lgkmcnt(0)
	v_and_b32_e32 v0, 0x78, v190
	s_xor_b32 s0, s0, s51
	v_add_u32_e32 v143, 64, v0
	v_add_u32_e32 v141, 0xc0, v0
	s_sub_i32 s14, s0, s51
	v_or_b32_e32 v155, v143, v196
	v_or_b32_e32 v135, 0x80, v190
	v_or_b32_e32 v151, v141, v196
	v_add_u32_e32 v199, v0, v196
	s_cmp_lt_i32 s14, 1
	v_lshlrev_b32_e32 v153, 11, v190
	v_lshrrev_b32_e32 v194, 1, v155
	v_lshrrev_b32_e32 v187, 1, v135
	v_lshrrev_b32_e32 v186, 1, v151
	v_lshlrev_b32_e32 v198, 2, v190
	v_lshlrev_b32_e32 v197, 2, v143
	v_and_b32_e32 v196, 31, v155
	v_lshlrev_b32_e32 v195, 2, v141
	v_add_u32_e32 v157, 64, v199
	s_barrier
	s_cbranch_scc1 .LBB0_1504
	s_waitcnt vmcnt(2)
	v_and_b32_e32 v4, 0x80, v198
	v_and_b32_e32 v5, 32, v188
	v_and_b32_e32 v8, 0x60, v187
	v_xor_b32_e32 v0, v188, v128
	v_xor_b32_e32 v1, v194, v128
	v_xor_b32_e32 v3, v186, v128
	v_or3_b32 v5, v5, v4, v193
	v_or3_b32 v4, v4, v8, v193
	v_and_b32_e32 v8, 0x80, v195
	v_and_b32_e32 v9, 0xe0, v186
	v_lshlrev_b32_e32 v0, 4, v0
	v_lshlrev_b32_e32 v1, 4, v1
	v_lshlrev_b32_e32 v3, 4, v3
	v_add_u32_e32 v9, v9, v8
	v_and_b32_e32 v0, 0x70, v0
	v_and_b32_e32 v2, 0x70, v1
	v_xor_b32_e32 v1, v187, v128
	v_and_b32_e32 v3, 0x70, v3
	v_and_or_b32 v9, v151, 31, v9
	v_bitop3_b32 v10, v188, v191, 3 bitop3:0x6c
	v_lshlrev_b32_e32 v1, 4, v1
	v_lshlrev_b32_e32 v139, 4, v10
	v_or_b32_e32 v10, v153, v0
	v_lshl_or_b32 v144, v5, 11, v0
	v_lshl_or_b32 v0, v9, 11, v3
	v_and_b32_e32 v1, 0x70, v1
	v_add_u32_e32 v134, 0xc3b1000, v10
	v_mov_b32_e32 v137, 0
	v_lshl_or_b32 v10, v155, 11, v2
	v_add_u32_e32 v150, 0x1080000, v0
	v_lshl_or_b32 v0, v130, 14, v133
	v_add_u32_e32 v138, 0xc3b1000, v10
	v_lshl_or_b32 v10, v135, 11, v1
	v_mov_b32_e32 v145, v137
	v_lshl_or_b32 v148, v4, 11, v1
	v_or_b32_e32 v4, v0, v2
	v_or_b32_e32 v1, v153, v1
	v_or_b32_e32 v0, v0, v3
	s_mov_b64 s[0:1], 0x80
	v_add_u32_e32 v154, 0xc3f1000, v1
	v_add_u32_e32 v156, 0xc411000, v0
	v_lshl_add_u64 v[0:1], s[86:87], 0, v[144:145]
	v_lshl_add_u64 v[158:159], v[0:1], 0, s[0:1]
	v_lshrrev_b32_e32 v0, 1, v157
	v_lshlrev_b16_e32 v1, 3, v130
	v_and_b32_e32 v6, 0x80, v197
	v_and_b32_e32 v0, 0xe0, v0
	v_bitop3_b16 v1, v1, v190, 7 bitop3:0xf8
	v_add_u32_e32 v152, 0xc3d1000, v4
	v_add_u32_e32 v0, v6, v0
	v_and_b32_e32 v4, 31, v1
	v_or_b32_e32 v0, v0, v4
	v_lshl_or_b32 v136, v0, 11, v2
	v_mov_b32_e32 v149, v137
	v_lshl_add_u64 v[0:1], s[86:87], 0, v[136:137]
	v_lshl_add_u64 v[160:161], v[0:1], 0, s[0:1]
	v_lshl_add_u64 v[0:1], s[86:87], 0, v[148:149]
	v_lshl_add_u64 v[162:163], v[0:1], 0, s[0:1]
	v_add_u32_e32 v0, 0xc0, v199
	v_lshrrev_b32_e32 v0, 1, v0
	v_and_b32_e32 v0, 0xe0, v0
	v_add_u32_e32 v0, v8, v0
	v_and_b32_e32 v7, 0x60, v194
	v_or_b32_e32 v0, v0, v4
	v_or3_b32 v7, v6, v7, v196
	v_add_u32_e32 v140, 0xc3b1000, v10
	v_lshl_or_b32 v10, v151, 11, v3
	s_add_u32 s6, s86, 0x80
	v_lshl_or_b32 v0, v0, 11, v3
	v_lshlrev_b32_e32 v147, 4, v192
	v_add_u32_e32 v142, 0xc3b1000, v10
	v_lshl_or_b32 v146, v7, 11, v2
	v_mov_b32_e32 v129, v137
	s_addc_u32 s7, s87, 0
	v_add_u32_e32 v164, 0x1080000, v0
	s_mov_b32 s9, 0
	v_mov_b32_e32 v165, 0x8000
	s_mov_b32 s15, 0x12000
	s_mov_b32 s16, 0xbfb8aa3b
	s_mov_b32 s17, 0x3f2aaaab
	v_mov_b32_e32 v184, 0x3ecc95a3
	s_mov_b32 s18, 0x3f317218
	s_mov_b32 s19, 0x7f800000
	s_mov_b32 s20, 0x33800000
	s_mov_b32 s21, 0x6170000
	s_mov_b32 s24, 0x6178000
	s_mov_b32 s25, 0x3d70000
	s_mov_b32 s26, 0x3d78000
	s_mov_b32 s27, 0x1971000
	s_mov_b32 s28, 0x1979000
	v_mov_b32_e32 v166, 0x3f317218
	v_mov_b32_e32 v185, 0x7f800000
	v_mov_b32_e32 v200, 0x7fc00000
	v_mov_b32_e32 v201, 0xff800000
	v_mov_b32_e32 v202, 4
	s_mov_b32 s29, 0
	s_branch .LBB0_1457

.LBB0_1567:
	s_or_b64 exec, exec, s[10:11]
	v_cvt_f32_u32_e32 v4, v2
	s_waitcnt vmcnt(0)
	v_readfirstlane_b32 s8, v3
	v_sub_u32_e32 v3, 0, v2
	v_rcp_iflag_f32_e32 v4, v4
	v_add_u32_e32 v5, s8, v1
	v_mul_f32_e32 v4, 0x4f7ffffe, v4
	v_cvt_u32_f32_e32 v4, v4
	v_mul_lo_u32 v1, v3, v4
	v_mul_hi_u32 v1, v4, v1
	v_add_u32_e32 v1, v4, v1
	v_mul_hi_u32 v1, v5, v1
	v_mul_lo_u32 v3, v1, v2
	v_sub_u32_e32 v3, v5, v3
	v_add_u32_e32 v4, 1, v1
	v_cmp_ge_u32_e32 vcc, v3, v2
	s_nop 1
	v_cndmask_b32_e32 v1, v1, v4, vcc
	v_sub_u32_e32 v4, v3, v2
	v_cndmask_b32_e32 v3, v3, v4, vcc
	v_add_u32_e32 v4, 1, v1
	v_cmp_ge_u32_e32 vcc, v3, v2
	v_add_u32_e32 v3, 1, v5
	s_nop 0
	v_cndmask_b32_e32 v1, v1, v4, vcc
	v_mul_lo_u32 v4, v2, v1
	v_add_u32_e32 v2, v4, v2
	v_cmp_ne_u32_e32 vcc, v3, v2
	s_and_saveexec_b64 s[8:9], vcc
	s_xor_b64 s[8:9], exec, s[8:9]
	s_cbranch_execz .LBB0_1581
	s_waitcnt lgkmcnt(0)
	buffer_inv sc1
	v_mov_b32_e32 v1, v0
	v_mov_b32_e32 v0, 0
	s_add_u32 s14, s86, 0xe7b10a0
	s_addc_u32 s15, s87, 0
	global_load_dword v0, v0, s[14:15] sc1
	s_waitcnt vmcnt(0)
	v_cmp_ne_u32_e32 vcc, v0, v1
	s_and_saveexec_b64 s[10:11], vcc
	s_cbranch_execz .LBB0_1580
	s_add_u32 s12, s86, 0xe7b1200
	s_addc_u32 s13, s87, 0
	s_mov_b32 s28, 1
	s_mov_b64 s[16:17], 0
	v_mov_b32_e32 v0, 0
	s_branch .LBB0_1571

.LBB0_1581:
	s_andn2_saveexec_b64 s[8:9], s[8:9]
	s_cbranch_execz .LBB0_1601
	s_mov_b64 s[8:9], exec
	buffer_wbl2 sc1
	buffer_inv sc1
	s_waitcnt lgkmcnt(0)
	s_waitcnt vmcnt(0)
	v_readfirstlane_b32 s99, v0
	s_add_u32 s100, s86, 0xe7b10a0
	s_addc_u32 s101, s87, 0
	v_mov_b32_e32 v0, 0
	v_mov_b32_e32 v2, 1
	global_atomic_add v0, v2, s[100:101]
	s_mov_b32 s98, 0

.Lxb_done_10:
	s_waitcnt vmcnt(0)
.LBB0_1601:
	s_or_b64 exec, exec, s[0:1]
	s_lshl_b32 s14, s2, 3
	v_add_u32_e32 v72, s14, v130
	s_movk_i32 s0, 0x900
	v_cmp_gt_i32_e32 vcc, s0, v72
	s_waitcnt lgkmcnt(0)
	s_barrier
	s_and_saveexec_b64 s[18:19], vcc
	s_cbranch_execz .LBB0_1608
	v_mbcnt_lo_u32_b32 v0, -1, 0
	s_waitcnt vmcnt(2)
	v_mbcnt_hi_u32_b32 v4, -1, v0
	v_bfrev_b32_e32 v0, 0.5
	v_lshl_or_b32 v5, v4, 2, v0
	v_lshlrev_b32_e32 v0, 2, v131
	v_mov_b32_e32 v1, 0
	v_and_b32_e32 v6, 64, v4
	v_lshl_add_u64 v[2:3], s[86:87], 0, v[0:1]
	v_add_u32_e32 v0, -1, v4
	v_cmp_lt_i32_e32 vcc, v0, v6
	s_mov_b64 s[0:1], 0xe7b5000
	v_lshl_add_u64 v[2:3], v[2:3], 0, s[0:1]
	v_cndmask_b32_e32 v0, v0, v4, vcc
	v_lshlrev_b32_e32 v8, 2, v0
	v_add_u32_e32 v0, -2, v4
	v_cmp_lt_i32_e64 s[0:1], v0, v6
	s_add_u32 s20, s86, 0x8171000
	s_addc_u32 s21, s87, 0
	v_cndmask_b32_e64 v0, v0, v4, s[0:1]
	v_lshlrev_b32_e32 v9, 2, v0
	v_add_u32_e32 v0, -4, v4
	v_cmp_lt_i32_e64 s[6:7], v0, v6
	s_lshl_b32 s24, s22, 3
	v_cmp_eq_u32_e32 vcc, 0, v131
	v_cndmask_b32_e64 v0, v0, v4, s[6:7]
	v_lshlrev_b32_e32 v10, 2, v0
	v_add_u32_e32 v0, -8, v4
	v_cmp_lt_i32_e64 s[8:9], v0, v6
	v_cmp_gt_u32_e64 s[0:1], 2, v131
	v_cmp_gt_u32_e64 s[6:7], 4, v131
	v_cndmask_b32_e64 v0, v0, v4, s[8:9]
	v_lshlrev_b32_e32 v11, 2, v0
	v_add_u32_e32 v0, -16, v4
	v_cmp_lt_i32_e64 s[10:11], v0, v6
	v_cmp_gt_u32_e64 s[8:9], 8, v131
	s_mov_b64 s[26:27], 0
	v_cndmask_b32_e64 v0, v0, v4, s[10:11]
	s_waitcnt vmcnt(0)
	v_lshlrev_b32_e32 v12, 2, v0
	v_subrev_u32_e32 v0, 32, v4
	v_cmp_lt_i32_e64 s[12:13], v0, v6
	v_cmp_gt_u32_e64 s[10:11], 16, v131
	s_mov_b32 s25, 0x38e38e39
	v_cndmask_b32_e64 v0, v0, v4, s[12:13]
	v_lshlrev_b32_e32 v13, 2, v0
	v_add_u32_e32 v0, s14, v130
	v_cmp_gt_u32_e64 s[12:13], 32, v131
	v_sub_u32_e32 v14, 17, v0
	s_movk_i32 s28, 0xffee
	s_movk_i32 s29, 0x7f
	v_not_b32_e32 v15, 63
	s_movk_i32 s30, 0x600
	s_movk_i32 s31, 0x8ff
	v_mov_b32_e32 v16, 0x4000
	v_mov_b32_e32 v4, v72
	s_branch .LBB0_1604

.LBB0_1629:
	s_or_b64 exec, exec, s[10:11]
	v_cvt_f32_u32_e32 v4, v2
	s_waitcnt vmcnt(0)
	v_readfirstlane_b32 s8, v3
	v_sub_u32_e32 v3, 0, v2
	v_rcp_iflag_f32_e32 v4, v4
	v_add_u32_e32 v5, s8, v1
	v_mul_f32_e32 v4, 0x4f7ffffe, v4
	v_cvt_u32_f32_e32 v4, v4
	v_mul_lo_u32 v1, v3, v4
	v_mul_hi_u32 v1, v4, v1
	v_add_u32_e32 v1, v4, v1
	v_mul_hi_u32 v1, v5, v1
	v_mul_lo_u32 v3, v1, v2
	v_sub_u32_e32 v3, v5, v3
	v_add_u32_e32 v4, 1, v1
	v_cmp_ge_u32_e32 vcc, v3, v2
	s_nop 1
	v_cndmask_b32_e32 v1, v1, v4, vcc
	v_sub_u32_e32 v4, v3, v2
	v_cndmask_b32_e32 v3, v3, v4, vcc
	v_add_u32_e32 v4, 1, v1
	v_cmp_ge_u32_e32 vcc, v3, v2
	v_add_u32_e32 v3, 1, v5
	s_nop 0
	v_cndmask_b32_e32 v1, v1, v4, vcc
	v_mul_lo_u32 v4, v2, v1
	v_add_u32_e32 v2, v4, v2
	v_cmp_ne_u32_e32 vcc, v3, v2
	s_and_saveexec_b64 s[8:9], vcc
	s_xor_b64 s[8:9], exec, s[8:9]
	s_cbranch_execz .LBB0_1643
	s_waitcnt lgkmcnt(0)
	buffer_inv sc1
	v_mov_b32_e32 v1, v0
	v_mov_b32_e32 v0, 0
	s_add_u32 s14, s86, 0xe7b10b0
	s_addc_u32 s15, s87, 0
	global_load_dword v0, v0, s[14:15] sc1
	s_waitcnt vmcnt(0)
	v_cmp_ne_u32_e32 vcc, v0, v1
	s_and_saveexec_b64 s[10:11], vcc
	s_cbranch_execz .LBB0_1642
	s_add_u32 s12, s86, 0xe7b1200
	s_addc_u32 s13, s87, 0
	s_mov_b32 s28, 1
	s_mov_b64 s[16:17], 0
	v_mov_b32_e32 v0, 0
	s_branch .LBB0_1633

.LBB0_1643:
	s_andn2_saveexec_b64 s[8:9], s[8:9]
	s_cbranch_execz .LBB0_1663
	s_mov_b64 s[8:9], exec
	buffer_wbl2 sc1
	buffer_inv sc1
	s_waitcnt lgkmcnt(0)
	s_waitcnt vmcnt(0)
	v_readfirstlane_b32 s99, v0
	s_add_u32 s100, s86, 0xe7b10b0
	s_addc_u32 s101, s87, 0
	v_mov_b32_e32 v0, 0
	v_mov_b32_e32 v2, 1
	global_atomic_add v0, v2, s[100:101]
	s_mov_b32 s98, 0

.Lxb_done_11:
	s_waitcnt vmcnt(0)
.LBB0_1663:
	s_or_b64 exec, exec, s[0:1]
	s_and_b64 vcc, exec, s[56:57]
	v_readfirstlane_b32 s6, v128
	s_waitcnt lgkmcnt(0)
	s_barrier
	s_cbranch_vccnz .LBB0_1748
	s_add_u32 s12, s86, 0x3d71000
	s_addc_u32 s13, s87, 0
	s_lshr_b32 s7, s6, 6
	s_and_b32 s34, s6, 0xffffffc0
	s_cmp_lt_u32 s6, 64
	s_cselect_b64 s[14:15], -1, 0
	s_cmpk_lt_u32 s6, 0x80
	s_cselect_b64 s[8:9], -1, 0
	s_cmpk_gt_u32 s6, 0x7f
	s_cselect_b64 s[18:19], -1, 0
	s_lshl_b32 s17, s6, 3
	s_and_b32 s38, s17, 0x200
	s_bfe_u32 s17, s6, 0x10006
	s_lshr_b32 s10, s6, 7
	s_lshr_b32 s11, s6, 5
	s_lshl_b32 s39, s17, 5
	s_lshl_b32 s17, s17, 6
	s_lshl_b32 s35, s10, 5
	s_and_b32 s11, s11, 2
	s_lshl_b32 s16, s7, 7
	s_add_i32 s38, s38, 0x21a00
	s_or_b32 s7, s7, 1
	s_or_b32 s41, s17, 0x15c00
	s_cmpk_gt_u32 s6, 0xff
	s_cselect_b64 s[20:21], -1, 0
	s_or_b32 s57, s17, 0x1e400
	s_cmp_le_u32 s11, s10
	s_cselect_b64 s[24:25], -1, 0
	s_lshl_b32 s58, s11, 5
	s_lshl_b32 s59, s11, 6
	s_or_b32 s17, s11, 1
	s_cmp_ge_u32 s11, s10
	s_cselect_b64 s[26:27], -1, 0
	s_lshl_b32 s60, s17, 6
	s_lshl_b32 s61, s17, 5
	s_cmp_gt_u32 s7, 2
	s_cselect_b64 s[30:31], -1, 0
	s_cmp_gt_u32 s7, 4
	s_cselect_b64 s[36:37], -1, 0
	s_cmpk_gt_u32 s6, 0x17f
	v_lshlrev_b32_e32 v0, 4, v128
	s_cselect_b64 s[42:43], -1, 0
	s_cmp_gt_u32 s7, 6
	v_or_b32_e32 v74, s34, v131
	v_and_b32_e32 v76, 48, v0
	s_cselect_b64 s[44:45], -1, 0
	s_add_u32 s62, s86, 0xe7b5000
	v_cndmask_b32_e64 v0, 0, 1, s[8:9]
	s_movk_i32 s0, 0x1200
	v_mov_b32_e32 v73, 0x21600
	v_ashrrev_i32_e32 v86, 2, v74
	v_mov_b32_e32 v1, 0
	s_addc_u32 s63, s87, 0
	s_add_i32 s16, s16, 0x1e400
	v_cmp_ne_u32_e64 s[6:7], 1, v0
	v_mbcnt_lo_u32_b32 v0, -1, 0
	v_cmp_gt_i32_e64 s[0:1], s0, v74
	v_lshl_or_b32 v77, v131, 2, v73
	v_sub_u32_e32 v87, 0xff, v86
	v_mov_b32_e32 v75, v1
	s_mov_b32 s40, 0x15c00
	s_mov_b32 s56, 0x1e400
	v_add_u32_e32 v88, 0xfffffe00, v74
	v_lshl_or_b32 v89, v131, 1, s16
	s_movk_i32 s64, 0xfff
	s_mov_b32 s46, 0
	v_lshlrev_b32_e32 v78, 1, v76
	v_mov_b32_e32 v79, v1
	s_mov_b32 s65, 0x83b1000
	v_mov_b32_e32 v90, 0x21700
	s_movk_i32 s68, 0x90
	s_movk_i32 s69, 0x110
	s_mov_b32 s72, 0x11800
	s_movk_i32 s73, 0x7fff
	v_mbcnt_hi_u32_b32 v91, -1, v0
	v_mov_b32_e32 v92, 0x21200
	v_mov_b32_e32 v93, 0x21800
	v_mov_b32_e32 v94, 0x20e00
	s_mov_b32 s74, s2
	s_branch .LBB0_1666

.LBB0_1766:
	s_or_b64 exec, exec, s[10:11]
	v_cvt_f32_u32_e32 v4, v2
	s_waitcnt vmcnt(0)
	v_readfirstlane_b32 s8, v3
	v_sub_u32_e32 v3, 0, v2
	v_rcp_iflag_f32_e32 v4, v4
	v_add_u32_e32 v5, s8, v1
	v_mul_f32_e32 v4, 0x4f7ffffe, v4
	v_cvt_u32_f32_e32 v4, v4
	v_mul_lo_u32 v1, v3, v4
	v_mul_hi_u32 v1, v4, v1
	v_add_u32_e32 v1, v4, v1
	v_mul_hi_u32 v1, v5, v1
	v_mul_lo_u32 v3, v1, v2
	v_sub_u32_e32 v3, v5, v3
	v_add_u32_e32 v4, 1, v1
	v_cmp_ge_u32_e32 vcc, v3, v2
	s_nop 1
	v_cndmask_b32_e32 v1, v1, v4, vcc
	v_sub_u32_e32 v4, v3, v2
	v_cndmask_b32_e32 v3, v3, v4, vcc
	v_add_u32_e32 v4, 1, v1
	v_cmp_ge_u32_e32 vcc, v3, v2
	v_add_u32_e32 v3, 1, v5
	s_nop 0
	v_cndmask_b32_e32 v1, v1, v4, vcc
	v_mul_lo_u32 v4, v2, v1
	v_add_u32_e32 v2, v4, v2
	v_cmp_ne_u32_e32 vcc, v3, v2
	s_and_saveexec_b64 s[8:9], vcc
	s_xor_b64 s[8:9], exec, s[8:9]
	s_cbranch_execz .LBB0_1780
	s_waitcnt lgkmcnt(0)
	buffer_inv sc1
	v_mov_b32_e32 v1, v0
	v_mov_b32_e32 v0, 0
	s_add_u32 s14, s86, 0xe7b10c0
	s_addc_u32 s15, s87, 0
	global_load_dword v0, v0, s[14:15] sc1
	s_waitcnt vmcnt(0)
	v_cmp_ne_u32_e32 vcc, v0, v1
	s_and_saveexec_b64 s[10:11], vcc
	s_cbranch_execz .LBB0_1779
	s_add_u32 s12, s86, 0xe7b1200
	s_addc_u32 s13, s87, 0
	s_mov_b32 s28, 1
	s_mov_b64 s[16:17], 0
	v_mov_b32_e32 v0, 0
	s_branch .LBB0_1770

.LBB0_1780:
	s_andn2_saveexec_b64 s[8:9], s[8:9]
	s_cbranch_execz .LBB0_1800
	s_mov_b64 s[8:9], exec
	buffer_wbl2 sc1
	buffer_inv sc1
	s_waitcnt lgkmcnt(0)
	s_waitcnt vmcnt(0)
	v_readfirstlane_b32 s99, v0
	s_add_u32 s100, s86, 0xe7b10c0
	s_addc_u32 s101, s87, 0
	v_mov_b32_e32 v0, 0
	v_mov_b32_e32 v2, 1
	global_atomic_add v0, v2, s[100:101]
	s_mov_b32 s98, 0

.Lxb_done_12:
	s_waitcnt vmcnt(0)
.LBB0_1800:
	s_or_b64 exec, exec, s[0:1]
	s_movk_i32 s0, 0x4000
	v_cmp_gt_i32_e32 vcc, s0, v72
	s_waitcnt lgkmcnt(0)
	s_barrier
	s_and_saveexec_b64 s[0:1], vcc
	s_cbranch_execz .LBB0_1803
	v_lshlrev_b32_e32 v0, 4, v128
	s_waitcnt vmcnt(2)
	v_and_b32_e32 v4, 0x3f0, v0
	v_mbcnt_lo_u32_b32 v0, -1, 0
	v_mbcnt_hi_u32_b32 v0, -1, v0
	v_and_b32_e32 v3, 64, v0
	v_xor_b32_e32 v2, 1, v0
	v_add_u32_e32 v3, 64, v3
	v_cmp_lt_i32_e32 vcc, v2, v3
	s_add_u32 s6, s86, 0x83b1000
	s_addc_u32 s7, s87, 0
	v_cndmask_b32_e32 v2, v0, v2, vcc
	v_lshlrev_b32_e32 v5, 2, v2
	v_xor_b32_e32 v2, 2, v0
	v_cmp_lt_i32_e32 vcc, v2, v3
	s_add_u32 s8, s86, 0xa3b1000
	s_addc_u32 s9, s87, 0
	v_cndmask_b32_e32 v2, v0, v2, vcc
	v_lshlrev_b32_e32 v10, 2, v2
	v_xor_b32_e32 v2, 4, v0
	v_cmp_lt_i32_e32 vcc, v2, v3
	s_add_u32 s10, s86, 0x6171000
	v_mov_b32_e32 v1, 0
	v_cndmask_b32_e32 v0, v0, v2, vcc
	v_lshlrev_b32_e32 v11, 2, v0
	v_lshlrev_b32_e32 v0, 2, v4
	s_addc_u32 s11, s87, 0
	v_lshl_add_u64 v[6:7], s[76:77], 0, v[0:1]
	s_lshl_b32 s14, s22, 3
	s_mov_b64 s[12:13], 0
	s_waitcnt vmcnt(0)
	v_mov_b32_e32 v12, 0x358637bd
	s_mov_b32 s15, 0x800000
	s_movk_i32 s16, 0x3fff

.LBB0_1821:
	s_or_b64 exec, exec, s[10:11]
	v_cvt_f32_u32_e32 v4, v2
	s_waitcnt vmcnt(0)
	v_readfirstlane_b32 s8, v3
	v_sub_u32_e32 v3, 0, v2
	v_rcp_iflag_f32_e32 v4, v4
	v_add_u32_e32 v5, s8, v1
	v_mul_f32_e32 v4, 0x4f7ffffe, v4
	v_cvt_u32_f32_e32 v4, v4
	v_mul_lo_u32 v1, v3, v4
	v_mul_hi_u32 v1, v4, v1
	v_add_u32_e32 v1, v4, v1
	v_mul_hi_u32 v1, v5, v1
	v_mul_lo_u32 v3, v1, v2
	v_sub_u32_e32 v3, v5, v3
	v_add_u32_e32 v4, 1, v1
	v_cmp_ge_u32_e32 vcc, v3, v2
	s_nop 1
	v_cndmask_b32_e32 v1, v1, v4, vcc
	v_sub_u32_e32 v4, v3, v2
	v_cndmask_b32_e32 v3, v3, v4, vcc
	v_add_u32_e32 v4, 1, v1
	v_cmp_ge_u32_e32 vcc, v3, v2
	v_add_u32_e32 v3, 1, v5
	s_nop 0
	v_cndmask_b32_e32 v1, v1, v4, vcc
	v_mul_lo_u32 v4, v2, v1
	v_add_u32_e32 v2, v4, v2
	v_cmp_ne_u32_e32 vcc, v3, v2
	s_and_saveexec_b64 s[8:9], vcc
	s_xor_b64 s[8:9], exec, s[8:9]
	s_cbranch_execz .LBB0_1835
	s_waitcnt lgkmcnt(0)
	buffer_inv sc1
	v_mov_b32_e32 v1, v0
	v_mov_b32_e32 v0, 0
	s_add_u32 s14, s86, 0xe7b10d0
	s_addc_u32 s15, s87, 0
	global_load_dword v0, v0, s[14:15] sc1
	s_waitcnt vmcnt(0)
	v_cmp_ne_u32_e32 vcc, v0, v1
	s_and_saveexec_b64 s[10:11], vcc
	s_cbranch_execz .LBB0_1834
	s_add_u32 s12, s86, 0xe7b1200
	s_addc_u32 s13, s87, 0
	s_mov_b32 s28, 1
	s_mov_b64 s[16:17], 0
	v_mov_b32_e32 v0, 0
	s_branch .LBB0_1825

.LBB0_1835:
	s_andn2_saveexec_b64 s[8:9], s[8:9]
	s_cbranch_execz .LBB0_1855
	s_mov_b64 s[8:9], exec
	buffer_wbl2 sc1
	buffer_inv sc1
	s_waitcnt lgkmcnt(0)
	s_waitcnt vmcnt(0)
	v_readfirstlane_b32 s99, v0
	s_add_u32 s100, s86, 0xe7b10d0
	s_addc_u32 s101, s87, 0
	v_mov_b32_e32 v0, 0
	v_mov_b32_e32 v2, 1
	global_atomic_add v0, v2, s[100:101]
	s_mov_b32 s98, 0

.Lxb_done_13:
	s_waitcnt vmcnt(0)
.LBB0_1855:
	s_or_b64 exec, exec, s[0:1]
	s_and_b64 vcc, exec, s[56:57]
	s_waitcnt lgkmcnt(0)
	s_barrier
	s_cbranch_vccnz .LBB0_1874
	v_xor_b32_e32 v1, v194, v128
	v_lshlrev_b32_e32 v1, 4, v1
	v_and_b32_e32 v2, 0x70, v1
	v_xor_b32_e32 v1, v187, v128
	v_lshlrev_b32_e32 v1, 4, v1
	v_and_b32_e32 v3, 0x70, v1
	v_xor_b32_e32 v1, v186, v128
	v_xor_b32_e32 v0, v188, v128
	v_lshlrev_b32_e32 v1, 4, v1
	v_lshlrev_b32_e32 v0, 4, v0
	v_and_b32_e32 v134, 0x70, v1
	s_waitcnt vmcnt(2)
	v_and_b32_e32 v4, 0x80, v198
	v_and_b32_e32 v1, 32, v188
	v_and_b32_e32 v0, 0x70, v0
	v_or3_b32 v1, v1, v4, v193
	v_bitop3_b32 v10, v188, v191, 3 bitop3:0x6c
	v_lshlrev_b32_e32 v137, 4, v10
	v_or_b32_e32 v10, v153, v0
	v_lshl_or_b32 v146, v1, 11, v0
	v_lshl_or_b32 v0, v130, 14, v133
	v_mov_b32_e32 v139, 0
	v_or_b32_e32 v1, v0, v2
	v_mov_b32_e32 v147, v139
	v_add_u32_e32 v154, 0xc3d1000, v1
	v_or_b32_e32 v1, v153, v3
	v_or_b32_e32 v0, v0, v134
	s_mov_b64 s[0:1], 0x80
	v_add_u32_e32 v156, 0xc3f1000, v1
	v_add_u32_e32 v158, 0xc411000, v0
	v_lshl_add_u64 v[0:1], s[86:87], 0, v[146:147]
	v_lshl_add_u64 v[160:161], v[0:1], 0, s[0:1]
	v_lshrrev_b32_e32 v0, 1, v157
	v_lshlrev_b16_e32 v1, 3, v130
	v_and_b32_e32 v5, 0x80, v197
	v_and_b32_e32 v6, 0x60, v194
	v_and_b32_e32 v0, 0xe0, v0
	v_bitop3_b16 v1, v1, v190, 7 bitop3:0xf8
	v_or3_b32 v6, v5, v6, v196
	v_add_u32_e32 v0, v5, v0
	v_and_b32_e32 v5, 31, v1
	v_or_b32_e32 v0, v0, v5
	v_lshl_or_b32 v138, v0, 11, v2
	v_lshl_add_u64 v[0:1], s[86:87], 0, v[138:139]
	v_lshl_add_u64 v[162:163], v[0:1], 0, s[0:1]
	v_or_b32_e32 v0, 0x80, v190
	v_lshrrev_b32_e32 v0, 1, v0
	v_and_b32_e32 v0, 0x60, v0
	v_or3_b32 v0, v4, v0, v193
	v_add_u32_e32 v136, 0xc3b1000, v10
	v_lshl_or_b32 v10, v155, 11, v2
	v_lshl_or_b32 v138, v0, 11, v3
	v_add_u32_e32 v140, 0xc3b1000, v10
	v_lshl_or_b32 v10, v135, 11, v3
	v_mov_b32_e32 v135, v139
	v_lshl_add_u64 v[0:1], s[86:87], 0, v[138:139]
	v_lshl_add_u64 v[164:165], v[0:1], 0, s[0:1]
	v_lshl_add_u64 v[0:1], s[86:87], 0, v[134:135]
	v_lshl_add_u64 v[166:167], v[0:1], 0, s[0:1]
	v_add_u32_e32 v0, 0xc0, v199
	v_lshrrev_b32_e32 v0, 1, v0
	v_and_b32_e32 v8, 0x80, v195
	v_and_b32_e32 v9, 0xe0, v186
	s_add_u32 s6, s86, 0x1938000
	v_and_b32_e32 v0, 0xe0, v0
	v_and_b32_e32 v7, 0x60, v187
	v_add_u32_e32 v9, v9, v8
	s_addc_u32 s7, s87, 0
	v_add_u32_e32 v0, v8, v0
	v_or3_b32 v7, v4, v7, v193
	v_and_or_b32 v9, v151, 31, v9
	v_add_u32_e32 v142, 0xc3b1000, v10
	v_lshl_or_b32 v10, v151, 11, v134
	v_lshl_or_b32 v148, v6, 11, v2
	v_mov_b32_e32 v6, 0x1700000
	s_add_u32 s8, s86, 0x80
	v_or_b32_e32 v0, v0, v5
	v_lshlrev_b32_e32 v145, 4, v192
	v_add_u32_e32 v144, 0xc3b1000, v10
	v_mov_b32_e32 v129, v139
	v_lshl_or_b32 v150, v7, 11, v3
	v_mov_b32_e32 v131, v139
	v_lshl_or_b32 v152, v9, 11, v6
	s_addc_u32 s9, s87, 0
	v_lshl_or_b32 v168, v0, 11, v6
	s_mov_b32 s16, 0x8000
	v_mov_b32_e32 v133, 0x8000
	s_mov_b32 s11, 0
	s_movk_i32 s17, 0xf800
	s_mov_b32 s18, 0x10000
	s_mov_b32 s19, 0x12000
	s_movk_i32 s20, 0x3fff
	s_mov_b32 s21, 0x18000
	s_mov_b32 s24, s2

.LBB0_1892:
	s_or_b64 exec, exec, s[10:11]
	v_cvt_f32_u32_e32 v4, v2
	s_waitcnt vmcnt(0)
	v_readfirstlane_b32 s8, v3
	v_sub_u32_e32 v3, 0, v2
	v_rcp_iflag_f32_e32 v4, v4
	v_add_u32_e32 v5, s8, v1
	v_mul_f32_e32 v4, 0x4f7ffffe, v4
	v_cvt_u32_f32_e32 v4, v4
	v_mul_lo_u32 v1, v3, v4
	v_mul_hi_u32 v1, v4, v1
	v_add_u32_e32 v1, v4, v1
	v_mul_hi_u32 v1, v5, v1
	v_mul_lo_u32 v3, v1, v2
	v_sub_u32_e32 v3, v5, v3
	v_add_u32_e32 v4, 1, v1
	v_cmp_ge_u32_e32 vcc, v3, v2
	s_nop 1
	v_cndmask_b32_e32 v1, v1, v4, vcc
	v_sub_u32_e32 v4, v3, v2
	v_cndmask_b32_e32 v3, v3, v4, vcc
	v_add_u32_e32 v4, 1, v1
	v_cmp_ge_u32_e32 vcc, v3, v2
	v_add_u32_e32 v3, 1, v5
	s_nop 0
	v_cndmask_b32_e32 v1, v1, v4, vcc
	v_mul_lo_u32 v4, v2, v1
	v_add_u32_e32 v2, v4, v2
	v_cmp_ne_u32_e32 vcc, v3, v2
	s_and_saveexec_b64 s[8:9], vcc
	s_xor_b64 s[8:9], exec, s[8:9]
	s_cbranch_execz .LBB0_1906
	s_waitcnt lgkmcnt(0)
	buffer_inv sc1
	v_mov_b32_e32 v1, v0
	v_mov_b32_e32 v0, 0
	s_add_u32 s14, s86, 0xe7b10e0
	s_addc_u32 s15, s87, 0
	global_load_dword v0, v0, s[14:15] sc1
	s_waitcnt vmcnt(0)
	v_cmp_ne_u32_e32 vcc, v0, v1
	s_and_saveexec_b64 s[10:11], vcc
	s_cbranch_execz .LBB0_1905
	s_add_u32 s12, s86, 0xe7b1200
	s_addc_u32 s13, s87, 0
	s_mov_b32 s28, 1
	s_mov_b64 s[16:17], 0
	v_mov_b32_e32 v0, 0
	s_branch .LBB0_1896

.LBB0_1906:
	s_andn2_saveexec_b64 s[8:9], s[8:9]
	s_cbranch_execz .LBB0_1926
	s_mov_b64 s[8:9], exec
	buffer_wbl2 sc1
	buffer_inv sc1
	s_waitcnt lgkmcnt(0)
	s_waitcnt vmcnt(0)
	v_readfirstlane_b32 s99, v0
	s_add_u32 s100, s86, 0xe7b10e0
	s_addc_u32 s101, s87, 0
	v_mov_b32_e32 v0, 0
	v_mov_b32_e32 v2, 1
	global_atomic_add v0, v2, s[100:101]
	s_mov_b32 s98, 0

.Lxb_done_14:
	s_waitcnt vmcnt(0)
.LBB0_1926:
	s_or_b64 exec, exec, s[0:1]
	s_movk_i32 s0, 0x4000
	v_cmp_gt_i32_e32 vcc, s0, v132
	s_waitcnt lgkmcnt(0)
	s_barrier
	s_and_saveexec_b64 s[0:1], vcc
	s_cbranch_execz .LBB0_1933
	v_mbcnt_lo_u32_b32 v1, -1, 0
	v_mbcnt_hi_u32_b32 v1, -1, v1
	v_and_b32_e32 v2, 64, v1
	v_add_u32_e32 v2, 64, v2
	v_xor_b32_e32 v3, 32, v1
	v_cmp_lt_i32_e32 vcc, v3, v2
	v_lshlrev_b32_e32 v0, 2, v128
	v_and_b32_e32 v0, 0xfc, v0
	v_cndmask_b32_e32 v3, v1, v3, vcc
	s_waitcnt vmcnt(5)
	v_lshlrev_b32_e32 v50, 2, v3
	v_xor_b32_e32 v3, 16, v1
	v_cmp_lt_i32_e32 vcc, v3, v2
	s_add_u32 s10, s66, 0x1000
	s_waitcnt vmcnt(3)
	v_mov_b32_e32 v25, 0
	v_cndmask_b32_e32 v3, v1, v3, vcc
	v_lshlrev_b32_e32 v51, 2, v3
	v_xor_b32_e32 v3, 8, v1
	v_cmp_lt_i32_e32 vcc, v3, v2
	s_addc_u32 s11, s67, 0
	s_waitcnt vmcnt(2)
	v_mov_b32_e32 v5, v25
	v_cndmask_b32_e32 v3, v1, v3, vcc
	v_lshlrev_b32_e32 v52, 2, v3
	v_xor_b32_e32 v3, 4, v1
	v_cmp_lt_i32_e32 vcc, v3, v2
	v_mov_b32_e32 v7, v25
	v_lshlrev_b32_e32 v24, 2, v0
	v_cndmask_b32_e32 v3, v1, v3, vcc
	v_lshlrev_b32_e32 v53, 2, v3
	v_xor_b32_e32 v3, 2, v1
	v_cmp_lt_i32_e32 vcc, v3, v2
	s_add_u32 s8, s86, 0x1939000
	v_lshl_add_u64 v[26:27], s[10:11], 0, v[24:25]
	v_cndmask_b32_e32 v3, v1, v3, vcc
	v_lshlrev_b32_e32 v54, 2, v3
	v_xor_b32_e32 v3, 1, v1
	v_cmp_lt_i32_e32 vcc, v3, v2
	v_or_b32_e32 v2, 0x100, v0
	v_lshlrev_b32_e32 v4, 2, v2
	s_waitcnt vmcnt(1)
	v_lshl_add_u64 v[28:29], s[10:11], 0, v[4:5]
	v_or_b32_e32 v4, 0x200, v0
	v_lshlrev_b32_e32 v6, 2, v4
	v_lshl_add_u64 v[30:31], s[10:11], 0, v[6:7]
	v_or_b32_e32 v6, 0x300, v0
	v_cndmask_b32_e32 v1, v1, v3, vcc
	v_lshlrev_b32_e32 v8, 2, v6
	v_mov_b32_e32 v9, v25
	v_lshl_add_u64 v[34:35], s[84:85], 0, v[24:25]
	v_lshlrev_b32_e32 v24, 1, v0
	s_mov_b64 s[6:7], 0x1000
	s_addc_u32 s9, s87, 0
	v_lshlrev_b32_e32 v55, 2, v1
	v_lshl_add_u64 v[32:33], s[10:11], 0, v[8:9]
	s_lshl_b32 s14, s22, 4
	v_lshl_add_u64 v[36:37], s[88:89], 0, v[24:25]
	s_mov_b64 s[10:11], 0
	s_movk_i32 s15, 0x3fff
	v_lshlrev_b32_e32 v38, 2, v0
	v_mov_b32_e32 v39, v25
	v_mov_b32_e32 v56, 0x358637bd
	s_mov_b32 s16, 0x800000
	v_lshlrev_b32_e32 v40, 2, v2
	v_mov_b32_e32 v41, v25
	v_lshlrev_b32_e32 v42, 2, v4
	v_mov_b32_e32 v43, v25
	v_lshlrev_b32_e32 v44, 2, v6
	v_mov_b32_e32 v45, v25
	s_branch .LBB0_1929

.LBB0_1951:
	s_or_b64 exec, exec, s[10:11]
	v_cvt_f32_u32_e32 v4, v2
	s_waitcnt vmcnt(0)
	v_readfirstlane_b32 s8, v3
	v_sub_u32_e32 v3, 0, v2
	v_rcp_iflag_f32_e32 v4, v4
	v_add_u32_e32 v5, s8, v1
	v_mul_f32_e32 v4, 0x4f7ffffe, v4
	v_cvt_u32_f32_e32 v4, v4
	v_mul_lo_u32 v1, v3, v4
	v_mul_hi_u32 v1, v4, v1
	v_add_u32_e32 v1, v4, v1
	v_mul_hi_u32 v1, v5, v1
	v_mul_lo_u32 v3, v1, v2
	v_sub_u32_e32 v3, v5, v3
	v_add_u32_e32 v4, 1, v1
	v_cmp_ge_u32_e32 vcc, v3, v2
	s_nop 1
	v_cndmask_b32_e32 v1, v1, v4, vcc
	v_sub_u32_e32 v4, v3, v2
	v_cndmask_b32_e32 v3, v3, v4, vcc
	v_add_u32_e32 v4, 1, v1
	v_cmp_ge_u32_e32 vcc, v3, v2
	v_add_u32_e32 v3, 1, v5
	s_nop 0
	v_cndmask_b32_e32 v1, v1, v4, vcc
	v_mul_lo_u32 v4, v2, v1
	v_add_u32_e32 v2, v4, v2
	v_cmp_ne_u32_e32 vcc, v3, v2
	s_and_saveexec_b64 s[8:9], vcc
	s_xor_b64 s[8:9], exec, s[8:9]
	s_cbranch_execz .LBB0_1965
	s_waitcnt lgkmcnt(0)
	buffer_inv sc1
	v_mov_b32_e32 v1, v0
	v_mov_b32_e32 v0, 0
	s_add_u32 s14, s86, 0xe7b10f0
	s_addc_u32 s15, s87, 0
	global_load_dword v0, v0, s[14:15] sc1
	s_waitcnt vmcnt(0)
	v_cmp_ne_u32_e32 vcc, v0, v1
	s_and_saveexec_b64 s[10:11], vcc
	s_cbranch_execz .LBB0_1964
	s_add_u32 s12, s86, 0xe7b1200
	s_addc_u32 s13, s87, 0
	s_mov_b32 s28, 1
	s_mov_b64 s[16:17], 0
	v_mov_b32_e32 v0, 0
	s_branch .LBB0_1955

.LBB0_1965:
	s_andn2_saveexec_b64 s[8:9], s[8:9]
	s_cbranch_execz .LBB0_1985
	s_mov_b64 s[8:9], exec
	buffer_wbl2 sc1
	buffer_inv sc1
	s_waitcnt lgkmcnt(0)
	s_waitcnt vmcnt(0)
	v_readfirstlane_b32 s99, v0
	s_add_u32 s100, s86, 0xe7b10f0
	s_addc_u32 s101, s87, 0
	v_mov_b32_e32 v0, 0
	v_mov_b32_e32 v2, 1
	global_atomic_add v0, v2, s[100:101]
	s_mov_b32 s98, 0

.Lxb_done_15:
	s_waitcnt vmcnt(0)
.LBB0_1985:
	s_or_b64 exec, exec, s[0:1]
	s_cmpk_gt_i32 s2, 0x5d7
	s_waitcnt lgkmcnt(0)
	s_barrier
	s_cbranch_scc1 .LBB0_2027
	v_xor_b32_e32 v0, v188, v128
	v_lshlrev_b32_e32 v0, 4, v0
	v_and_b32_e32 v132, 0x70, v0
	v_and_b32_e32 v0, 0x7f, v155
	v_add_u32_e32 v136, -1, v0
	v_xor_b32_e32 v0, v194, v128
	v_mov_b32_e32 v133, 0
	v_lshlrev_b32_e32 v0, 4, v0
	v_and_b32_e32 v0, 0x70, v0
	v_mov_b32_e32 v1, v133
	v_lshl_add_u64 v[138:139], s[88:89], 0, v[0:1]
	v_and_b32_e32 v1, 0x7f, v151
	v_add_u32_e32 v139, -1, v1
	v_xor_b32_e32 v1, v186, v128
	v_lshlrev_b32_e32 v1, 4, v1
	v_and_b32_e32 v140, 0x70, v1
	v_and_b32_e32 v1, 0x80, v198
	v_and_b32_e32 v2, 32, v188
	v_or3_b32 v3, v2, v1, v193
	v_or3_b32 v1, v2, v193, v1
	s_waitcnt vmcnt(2)
	v_and_b32_e32 v6, 0x80, v195
	v_and_b32_e32 v2, 0xe0, v186
	v_add_u32_e32 v2, v2, v6
	v_lshl_add_u64 v[134:135], s[88:89], 0, v[132:133]
	v_lshrrev_b32_e32 v137, 7, v141
	v_mov_b32_e32 v141, v133
	v_and_or_b32 v2, v151, 31, v2
	v_lshrrev_b32_e32 v135, 7, v143
	v_lshl_add_u64 v[142:143], s[88:89], 0, v[140:141]
	v_lshlrev_b32_e32 v1, 11, v1
	v_lshlrev_b32_e32 v144, 11, v2
	v_bitop3_b32 v2, v188, v191, 3 bitop3:0x6c
	v_lshl_or_b32 v146, v3, 11, v132
	v_mov_b32_e32 v147, v133
	s_mov_b32 s0, 0x20000
	v_lshlrev_b32_e32 v143, 4, v2
	v_or3_b32 v150, v1, v132, s0
	s_mov_b64 s[0:1], 0x80
	v_lshl_add_u64 v[2:3], s[86:87], 0, v[146:147]
	v_readlane_b32 s4, v252, 0
	v_lshl_add_u64 v[152:153], v[2:3], 0, s[0:1]
	v_lshrrev_b32_e32 v1, 1, v157
	v_lshlrev_b16_e32 v2, 3, v130
	v_readlane_b32 s6, v252, 2
	v_readlane_b32 s7, v252, 3
	v_readlane_b32 s14, v252, 10
	v_readlane_b32 s15, v252, 11
	v_and_b32_e32 v4, 0x80, v197
	v_and_b32_e32 v1, 0xe0, v1
	v_bitop3_b16 v2, v2, v190, 7 bitop3:0xf8
	v_readlane_b32 s8, v252, 4
	v_readlane_b32 s9, v252, 5
	v_readlane_b32 s16, v252, 12
	v_readlane_b32 s17, v252, 13
	s_mov_b64 s[14:15], s[6:7]
	v_add_u32_e32 v1, v4, v1
	v_and_b32_e32 v2, 31, v2
	s_mov_b64 s[16:17], s[8:9]
	s_add_u32 s8, s14, 0x8400
	v_and_b32_e32 v5, 0x60, v194
	v_or_b32_e32 v1, v1, v2
	v_readlane_b32 s10, v252, 6
	s_addc_u32 s9, s15, 0
	v_or3_b32 v5, v4, v5, v196
	v_lshl_or_b32 v132, v1, 11, v0
	v_readlane_b32 s11, v252, 7
	s_add_u32 s10, s16, 0x2c00
	v_lshl_or_b32 v148, v5, 11, v0
	v_lshl_add_u64 v[0:1], s[86:87], 0, v[132:133]
	v_readlane_b32 s12, v252, 8
	s_addc_u32 s11, s17, 0
	v_lshl_add_u64 v[130:131], v[0:1], 0, s[0:1]
	v_lshl_add_u64 v[0:1], s[86:87], 0, v[140:141]
	v_readlane_b32 s13, v252, 9
	s_add_u32 s12, s14, 0xb000
	v_lshl_add_u64 v[156:157], v[0:1], 0, s[0:1]
	v_add_u32_e32 v0, 0xc0, v199
	s_addc_u32 s13, s15, 0
	v_lshrrev_b32_e32 v0, 1, v0
	s_add_u32 s14, s14, 0xdc00
	v_and_b32_e32 v0, 0xe0, v0
	v_readlane_b32 s18, v252, 14
	s_addc_u32 s15, s15, 0
	v_add_u32_e32 v0, v6, v0
	v_readlane_b32 s19, v252, 15
	s_add_u32 s18, s86, 0x80
	v_or_b32_e32 v0, v0, v2
	v_add_u32_e32 v129, -1, v190
	v_lshlrev_b32_e32 v145, 4, v192
	s_addc_u32 s19, s87, 0
	v_or_b32_e32 v154, 0x20000, v146
	v_lshlrev_b32_e32 v158, 11, v0
	s_mov_b32 s16, 0x78787879
	s_movk_i32 s17, 0x87
	s_mov_b32 s24, 0xaaaaaaab
	s_movk_i32 s25, 0x88
	s_movk_i32 s26, 0x7e
	s_movk_i32 s27, 0x800
	v_mov_b32_e32 v147, s92
	v_mov_b32_e32 v149, 0x8000
	s_movk_i32 s28, 0xf800
	s_mov_b32 s29, 0x12000
	s_movk_i32 s30, 0x1600
	v_mov_b32_e32 v159, 0x4000
	v_mov_b32_e32 v176, 3
	v_mov_b32_e32 v177, 7
	s_mov_b32 s31, s2
	v_readlane_b32 s5, v252, 1
	s_branch .LBB0_1988

.LBB0_2045:
	s_or_b64 exec, exec, s[10:11]
	v_cvt_f32_u32_e32 v4, v2
	s_waitcnt vmcnt(0)
	v_readfirstlane_b32 s3, v3
	v_sub_u32_e32 v3, 0, v2
	v_rcp_iflag_f32_e32 v4, v4
	v_add_u32_e32 v5, s3, v1
	v_mul_f32_e32 v4, 0x4f7ffffe, v4
	v_cvt_u32_f32_e32 v4, v4
	v_mul_lo_u32 v1, v3, v4
	v_mul_hi_u32 v1, v4, v1
	v_add_u32_e32 v1, v4, v1
	v_mul_hi_u32 v1, v5, v1
	v_mul_lo_u32 v3, v1, v2
	v_sub_u32_e32 v3, v5, v3
	v_add_u32_e32 v4, 1, v1
	v_cmp_ge_u32_e32 vcc, v3, v2
	s_nop 1
	v_cndmask_b32_e32 v1, v1, v4, vcc
	v_sub_u32_e32 v4, v3, v2
	v_cndmask_b32_e32 v3, v3, v4, vcc
	v_add_u32_e32 v4, 1, v1
	v_cmp_ge_u32_e32 vcc, v3, v2
	v_add_u32_e32 v3, 1, v5
	s_nop 0
	v_cndmask_b32_e32 v1, v1, v4, vcc
	v_mul_lo_u32 v4, v2, v1
	v_add_u32_e32 v2, v4, v2
	v_cmp_ne_u32_e32 vcc, v3, v2
	s_and_saveexec_b64 s[8:9], vcc
	s_xor_b64 s[8:9], exec, s[8:9]
	s_cbranch_execz .LBB0_2059
	s_waitcnt lgkmcnt(0)
	buffer_inv sc1
	v_mov_b32_e32 v1, v0
	v_mov_b32_e32 v0, 0
	s_add_u32 s14, s86, 0xe7b1100
	s_addc_u32 s15, s87, 0
	global_load_dword v0, v0, s[14:15] sc1
	s_waitcnt vmcnt(0)
	v_cmp_ne_u32_e32 vcc, v0, v1
	s_and_saveexec_b64 s[10:11], vcc
	s_cbranch_execz .LBB0_2058
	s_add_u32 s12, s86, 0xe7b1200
	s_addc_u32 s13, s87, 0
	s_mov_b32 s3, 1
	s_mov_b64 s[16:17], 0
	v_mov_b32_e32 v0, 0
	s_branch .LBB0_2049

.LBB0_2053:
	global_load_dword v2, v0, s[14:15] sc1
	s_add_i32 s3, s3, 1
	s_mov_b64 s[24:25], -1
	s_waitcnt vmcnt(0)
	v_cmp_eq_u32_e32 vcc, v2, v1
	s_orn2_b64 s[20:21], vcc, exec
	s_branch .LBB0_2048

.LBB0_2059:
	s_andn2_saveexec_b64 s[8:9], s[8:9]
	s_cbranch_execz .LBB0_2079
	s_mov_b64 s[8:9], exec
	buffer_wbl2 sc1
	buffer_inv sc1
	s_waitcnt lgkmcnt(0)
	s_waitcnt vmcnt(0)
	v_readfirstlane_b32 s99, v0
	s_add_u32 s100, s86, 0xe7b1100
	s_addc_u32 s101, s87, 0
	v_mov_b32_e32 v0, 0
	v_mov_b32_e32 v2, 1
	global_atomic_add v0, v2, s[100:101]
	s_mov_b32 s98, 0

.Lxb_done_16:
	s_waitcnt vmcnt(0)
.LBB0_2079:
	s_or_b64 exec, exec, s[0:1]
	s_and_b64 vcc, exec, s[56:57]
	s_waitcnt lgkmcnt(0)
	s_barrier
	s_cbranch_vccnz .LBB0_2098
	s_waitcnt vmcnt(6)
	v_xor_b32_e32 v3, v186, v128
	v_lshlrev_b32_e32 v3, 3, v3
	s_waitcnt vmcnt(2)
	v_and_b32_e32 v5, 0x80, v197
	v_and_b32_e32 v6, 0x60, v194
	v_and_b32_e32 v130, 56, v3
	v_and_b32_e32 v3, 0x80, v198
	v_and_b32_e32 v4, 32, v188
	v_or3_b32 v5, v5, v6, v196
	v_and_b32_e32 v6, 0x60, v187
	v_or3_b32 v4, v4, v3, v193
	v_or3_b32 v3, v3, v6, v193
	v_and_b32_e32 v6, 0x80, v195
	v_and_b32_e32 v7, 0xe0, v186
	v_xor_b32_e32 v0, v188, v128
	v_add_u32_e32 v6, v7, v6
	v_bitop3_b32 v7, v188, v191, 3 bitop3:0x6c
	v_lshlrev_b32_e32 v0, 4, v0
	v_lshlrev_b32_e32 v129, 4, v7
	s_movk_i32 s0, 0x1600
	v_mov_b32_e32 v7, 0x3831000
	v_and_b32_e32 v0, 0x70, v0
	v_xor_b32_e32 v1, v194, v128
	v_mad_u32_u24 v8, v190, s0, v7
	v_mul_u32_u24_e32 v4, 0x1600, v4
	v_lshlrev_b32_e32 v1, 4, v1
	v_or_b32_e32 v134, v0, v8
	v_or_b32_e32 v0, v4, v0
	v_and_b32_e32 v1, 0x70, v1
	v_xor_b32_e32 v2, v187, v128
	v_add_u32_e32 v142, 0xb00000, v0
	v_mul_u32_u24_e32 v0, 0x1600, v5
	v_lshlrev_b32_e32 v2, 4, v2
	v_or_b32_e32 v0, v0, v1
	v_and_b32_e32 v2, 0x70, v2
	v_add_u32_e32 v144, 0xb00000, v0
	v_mul_u32_u24_e32 v0, 0x1600, v3
	v_mov_b32_e32 v133, 0
	s_add_u32 s4, s86, 0x193b000
	v_or_b32_e32 v0, v0, v2
	v_and_or_b32 v6, v151, 31, v6
	s_addc_u32 s5, s87, 0
	v_mul_u32_u24_e32 v9, 0x1600, v155
	v_mad_u32_u24 v140, v151, s0, v7
	v_add_u32_e32 v146, 0xb00000, v0
	v_mov_b32_e32 v0, 0xb00000
	v_lshlrev_b32_e32 v150, 1, v130
	v_mov_b32_e32 v151, v133
	v_or_b32_e32 v9, v9, v1
	v_or_b32_e32 v8, v8, v2
	v_mad_u32_u24 v148, v6, s0, v0
	s_mov_b64 s[0:1], 0x80
	s_add_u32 s6, s86, 0x80
	v_lshl_add_u64 v[0:1], s[86:87], 0, v[150:151]
	v_lshlrev_b32_e32 v131, 4, v192
	v_add_u32_e32 v136, 0x3831000, v9
	v_add_u32_e32 v138, 0xb0000, v8
	s_addc_u32 s7, s87, 0
	v_lshl_add_u64 v[152:153], v[0:1], 0, s[0:1]
	s_mov_b32 s3, 0x8000
	v_mov_b32_e32 v135, 0x8000
	s_mov_b32 s12, 0x10000
	s_mov_b32 s13, 0x12000
	s_movk_i32 s14, 0x3fff
	s_mov_b32 s15, 0x18000

	.amdhsa_kernel _Z14fwd_megakernel6Params
		.amdhsa_group_segment_fixed_size 147472
		.amdhsa_private_segment_fixed_size 0
		.amdhsa_kernarg_size 496
		.amdhsa_user_sgpr_count 2
		.amdhsa_user_sgpr_dispatch_ptr 0
		.amdhsa_user_sgpr_queue_ptr 0
		.amdhsa_user_sgpr_kernarg_segment_ptr 1
		.amdhsa_user_sgpr_dispatch_id 0
		.amdhsa_user_sgpr_kernarg_preload_length 0
		.amdhsa_user_sgpr_kernarg_preload_offset 0
		.amdhsa_user_sgpr_private_segment_size 0
		.amdhsa_uses_dynamic_stack 0
		.amdhsa_enable_private_segment 0
		.amdhsa_system_sgpr_workgroup_id_x 1
		.amdhsa_system_sgpr_workgroup_id_y 0
		.amdhsa_system_sgpr_workgroup_id_z 0
		.amdhsa_system_sgpr_workgroup_info 0
		.amdhsa_system_vgpr_workitem_id 2
		.amdhsa_next_free_vgpr 256
		.amdhsa_next_free_sgpr 102
		.amdhsa_accum_offset 256
		.amdhsa_reserve_vcc 1
		.amdhsa_float_round_mode_32 0
		.amdhsa_float_round_mode_16_64 0
		.amdhsa_float_denorm_mode_32 3
		.amdhsa_float_denorm_mode_16_64 3
		.amdhsa_dx10_clamp 1
		.amdhsa_ieee_mode 1
		.amdhsa_fp16_overflow 0
		.amdhsa_tg_split 0
		.amdhsa_exception_fp_ieee_invalid_op 0
		.amdhsa_exception_fp_denorm_src 0
		.amdhsa_exception_fp_ieee_div_zero 0
		.amdhsa_exception_fp_ieee_overflow 0
		.amdhsa_exception_fp_ieee_underflow 0
		.amdhsa_exception_fp_ieee_inexact 0
		.amdhsa_exception_int_div_zero 0
	.end_amdhsa_kernel

amdhsa.kernels:
  - .agpr_count:     0
    .args:
      - .offset:         0
        .size:           240
        .value_kind:     by_value
      - .offset:         240
        .size:           4
        .value_kind:     hidden_block_count_x
      - .offset:         244
        .size:           4
        .value_kind:     hidden_block_count_y
      - .offset:         248
        .size:           4
        .value_kind:     hidden_block_count_z
      - .offset:         252
        .size:           2
        .value_kind:     hidden_group_size_x
      - .offset:         254
        .size:           2
        .value_kind:     hidden_group_size_y
      - .offset:         256
        .size:           2
        .value_kind:     hidden_group_size_z
      - .offset:         258
        .size:           2
        .value_kind:     hidden_remainder_x
      - .offset:         260
        .size:           2
        .value_kind:     hidden_remainder_y
      - .offset:         262
        .size:           2
        .value_kind:     hidden_remainder_z
      - .offset:         280
        .size:           8
        .value_kind:     hidden_global_offset_x
      - .offset:         288
        .size:           8
        .value_kind:     hidden_global_offset_y
      - .offset:         296
        .size:           8
        .value_kind:     hidden_global_offset_z
      - .offset:         304
        .size:           2
        .value_kind:     hidden_grid_dims
      - .offset:         328
        .size:           8
        .value_kind:     hidden_multigrid_sync_arg
    .group_segment_fixed_size: 147472
    .kernarg_segment_align: 8
    .kernarg_segment_size: 496
    .language:       OpenCL C
    .language_version:
      - 2
      - 0
    .max_flat_workgroup_size: 512
    .name:           _Z14fwd_megakernel6Params
    .private_segment_fixed_size: 0
    .sgpr_count:     108
    .sgpr_spill_count: 64
    .symbol:         _Z14fwd_megakernel6Params.kd
    .uniform_work_group_size: 1
    .uses_dynamic_stack: false
    .vgpr_count:     256
    .vgpr_spill_count: 0
    .wavefront_size: 64
